# post-phase loop loads de-serialized (own dest per ushort load, single wait); pool item weight/d fragments preloaded before the 16 MFMAs
# speedup vs baseline: 1.0261x; 1.0183x over previous
; #define LAS __attribute__((address_space(3)))
; __device__ __forceinline__ unsigned f2bf(float f) { unsigned u = __builtin_bit_cast(unsigned, f); return (u + 0x7fffu + ((u >> 16) & 1u)) >> 16; }
; __device__ __forceinline__ float bf1(bf16 h) { return __uint_as_float(((unsigned)h) << 16); }
; __device__ __forceinline__ void pool_item(const Args& A, const Ctx& C0, int l, int row0, int t0, int pos0, const float* hist, float* outpool) {
;     ...
;     { const int c = C.tid, gc = c >> 7, wdc = 2 << gc;
;       float s = 0.f;
;       for (int i = 0; i < wdc; ++i) s += bf1(P[(15 - i) * PP + c]);
; #pragma unroll 4
;       for (int t = 0; t < 32; ++t) { const int pos = pos0 + t; const float inv = 1.f / (float)((pos + 1) < wdc ? (pos + 1) : wdc);
;           const float cur = bf1(P[(15 + t) * PP + c]);
;           Dm[t * PP + c] = (bf16)f2bf(s * inv - cur);
;           s += bf1(P[(16 + t) * PP + c]) - bf1(P[(16 + t - wdc) * PP + c]); } }
;     __syncthreads();
;     const int g = C.wave & 3, ddh = C.wave >> 2, tk = C.lane & 31, h = C.lane >> 5;
;     const bf16* PW = WS_PTR(const bf16, WS_PWT) + (size_t)(l * 4 + g) * 128 * 128;
;     f32x16 acc[2];
; #pragma unroll
;     for (int dt = 0; dt < 2; ++dt)
; #pragma unroll
;         for (int r = 0; r < 16; ++r) acc[dt][r] = 0.f;
; #pragma unroll
;     for (int ks = 0; ks < 8; ++ks) { const bf16x8 df = *(const LAS bf16x8*)(Dm + tk * PP + g * 128 + ks * 16 + 8 * h);
; #pragma unroll
;         for (int dt = 0; dt < 2; ++dt) { const bf16x8 af = *(const bf16x8*)(PW + (size_t)(ddh * 64 + dt * 32 + tk) * 128 + ks * 16 + 8 * h);
;             acc[dt] = __builtin_amdgcn_mfma_f32_32x32x16_bf16(af, df, acc[dt], 0, 0, 0); }
;     }
.LBB0_757:
	s_add_i32 s1, s16, s0
	s_add_i32 s2, s1, 1
	v_min_i32_e32 v3, s2, v0
	v_cvt_f32_i32_e32 v3, v3
	s_waitcnt lgkmcnt(0)
	v_lshlrev_b32_e32 v5, 16, v5
	s_add_i32 s0, s0, 4
	v_div_scale_f32 v7, s[2:3], v3, v3, 1.0
	v_rcp_f32_e32 v8, v7
	s_add_i32 s2, s1, 2
	v_fma_f32 v9, -v7, v8, 1.0
	v_fmac_f32_e32 v8, v9, v8
	v_div_scale_f32 v9, vcc, 1.0, v3, 1.0
	v_mul_f32_e32 v10, v9, v8
	v_fma_f32 v11, -v7, v10, v9
	v_fmac_f32_e32 v10, v11, v8
	v_fma_f32 v7, -v7, v10, v9
	v_div_fmas_f32 v7, v7, v8, v10
	v_div_fixup_f32 v3, v7, v3, 1.0
	v_fma_f32 v3, v4, v3, -v5
	v_bfe_u32 v5, v3, 16, 1
	v_add3_u32 v3, v3, v5, s33
	ds_write_b16_d16_hi v6, v3 offset:33280
	v_add_u32_e32 v3, v6, v2
	ds_read_u16 v5, v3 offset:1040
	ds_read_u16 v7, v6 offset:1040
	s_waitcnt lgkmcnt(1)
	v_lshlrev_b32_e32 v5, 16, v5
	s_waitcnt lgkmcnt(0)
	v_lshlrev_b32_e32 v7, 16, v7
	v_sub_f32_e32 v5, v7, v5
	v_add_f32_e32 v4, v4, v5
	v_min_i32_e32 v5, s2, v0
	v_cvt_f32_i32_e32 v5, v5
	v_div_scale_f32 v8, s[2:3], v5, v5, 1.0
	v_rcp_f32_e32 v9, v8
	s_add_i32 s2, s1, 3
	s_add_i32 s1, s1, 4
	s_cmp_eq_u32 s0, 32
	v_fma_f32 v10, -v8, v9, 1.0
	v_fmac_f32_e32 v9, v10, v9
	v_div_scale_f32 v10, vcc, 1.0, v5, 1.0
	v_mul_f32_e32 v11, v10, v9
	v_fma_f32 v12, -v8, v11, v10
	v_fmac_f32_e32 v11, v12, v9
	v_fma_f32 v8, -v8, v11, v10
	v_div_fmas_f32 v8, v8, v9, v11
	v_div_fixup_f32 v5, v8, v5, 1.0
	v_fma_f32 v5, v4, v5, -v7
	v_bfe_u32 v7, v5, 16, 1
	v_add3_u32 v5, v5, v7, s33
	ds_write_b16_d16_hi v6, v5 offset:34320
	ds_read_u16 v5, v3 offset:2080
	ds_read_u16 v7, v6 offset:2080
	s_waitcnt lgkmcnt(1)
	v_lshlrev_b32_e32 v5, 16, v5
	s_waitcnt lgkmcnt(0)
	v_lshlrev_b32_e32 v7, 16, v7
	v_sub_f32_e32 v5, v7, v5
	v_add_f32_e32 v4, v4, v5
	v_min_i32_e32 v5, s2, v0
	v_cvt_f32_i32_e32 v5, v5
	v_div_scale_f32 v8, s[2:3], v5, v5, 1.0
	v_rcp_f32_e32 v9, v8
	s_nop 0
	v_fma_f32 v10, -v8, v9, 1.0
	v_fmac_f32_e32 v9, v10, v9
	v_div_scale_f32 v10, vcc, 1.0, v5, 1.0
	v_mul_f32_e32 v11, v10, v9
	v_fma_f32 v12, -v8, v11, v10
	v_fmac_f32_e32 v11, v12, v9
	v_fma_f32 v8, -v8, v11, v10
	v_div_fmas_f32 v8, v8, v9, v11
	v_div_fixup_f32 v5, v8, v5, 1.0
	v_fma_f32 v5, v4, v5, -v7
	v_bfe_u32 v7, v5, 16, 1
	v_add3_u32 v5, v5, v7, s33
	ds_write_b16_d16_hi v6, v5 offset:35360
	ds_read_u16 v5, v3 offset:3120
	ds_read_u16 v7, v6 offset:3120
	s_waitcnt lgkmcnt(1)
	v_lshlrev_b32_e32 v5, 16, v5
	s_waitcnt lgkmcnt(0)
	v_lshlrev_b32_e32 v7, 16, v7
	v_sub_f32_e32 v5, v7, v5
	v_add_f32_e32 v4, v4, v5
	v_min_i32_e32 v5, s1, v0
	v_cvt_f32_i32_e32 v5, v5
	v_div_scale_f32 v8, s[2:3], v5, v5, 1.0
	v_rcp_f32_e32 v9, v8
	s_nop 0
	v_fma_f32 v10, -v8, v9, 1.0
	v_fmac_f32_e32 v9, v10, v9
	v_div_scale_f32 v10, vcc, 1.0, v5, 1.0
	v_mul_f32_e32 v11, v10, v9
	v_fma_f32 v12, -v8, v11, v10
	v_fmac_f32_e32 v11, v12, v9
	v_fma_f32 v8, -v8, v11, v10
	v_div_fmas_f32 v8, v8, v9, v11
	v_div_fixup_f32 v5, v8, v5, 1.0
	v_fma_f32 v5, v4, v5, -v7
	v_bfe_u32 v7, v5, 16, 1
	v_add3_u32 v5, v5, v7, s33
	ds_write_b16_d16_hi v6, v5 offset:36400
	ds_read_u16 v5, v6 offset:4160
	ds_read_u16 v3, v3 offset:4160
	v_add_u32_e32 v7, 0x1040, v6
	s_waitcnt lgkmcnt(1)
	v_lshlrev_b32_e32 v6, 16, v5
	s_waitcnt lgkmcnt(0)
	v_lshlrev_b32_e32 v3, 16, v3
	v_sub_f32_e32 v3, v6, v3
	v_add_f32_e32 v4, v4, v3
	v_mov_b32_e32 v6, v7
	s_cbranch_scc0 .LBB0_757
	s_bfe_u32 s0, s75, 0x20006
	v_readlane_b32 s1, v255, 46
	s_or_b32 s2, s0, s1
	s_ashr_i32 s3, s2, 31
	s_lshl_b64 s[2:3], s[2:3], 15
	s_add_u32 s2, s24, s2
	v_bfe_u32 v48, v34, 5, 1
	v_and_b32_e32 v49, 31, v34
	s_addc_u32 s3, s25, s3
	s_lshl_b32 s1, s0, 8
	v_mul_u32_u24_e32 v2, 0x410, v49
	s_add_i32 s1, s1, 0
	v_lshlrev_b32_e32 v0, 4, v48
	v_add3_u32 v50, s1, v2, v0
	s_ashr_i32 s1, s75, 2
	s_andn2_b32 s1, s1, 63
	v_or_b32_e32 v10, s1, v49
	v_lshl_add_u64 v[2:3], s[2:3], 0, v[0:1]
	s_mov_b64 s[2:3], 0x7900000
	v_ashrrev_i32_e32 v11, 31, v10
	v_lshl_add_u64 v[12:13], v[2:3], 0, s[2:3]
	v_lshlrev_b64 v[2:3], 8, v[10:11]
	v_lshl_add_u64 v[44:45], v[12:13], 0, v[2:3]
	s_barrier
	s_lshl_b32 s0, s0, 7
	s_add_i32 s0, s0, s1
	v_add_u32_e32 v0, s10, v49
	s_cmp_lg_u64 s[60:61], 0
	s_movk_i32 s2, 0x1e00
	v_or_b32_e32 v2, 32, v10
	v_ashrrev_i32_e32 v3, 31, v2
	v_lshlrev_b64 v[2:3], 8, v[2:3]
	v_lshl_add_u64 v[46:47], v[12:13], 0, v[2:3]
	global_load_dwordx4 v[148:151], v[44:45], off
	global_load_dwordx4 v[180:183], v[46:47], off
	global_load_dwordx4 v[152:155], v[44:45], off offset:32
	global_load_dwordx4 v[188:191], v[46:47], off offset:32
	global_load_dwordx4 v[156:159], v[44:45], off offset:64
	global_load_dwordx4 v[192:195], v[46:47], off offset:64
	global_load_dwordx4 v[160:163], v[44:45], off offset:96
	global_load_dwordx4 v[196:199], v[46:47], off offset:96
	global_load_dwordx4 v[164:167], v[44:45], off offset:128
	global_load_dwordx4 v[200:203], v[46:47], off offset:128
	global_load_dwordx4 v[168:171], v[44:45], off offset:160
	global_load_dwordx4 v[208:211], v[46:47], off offset:160
	global_load_dwordx4 v[172:175], v[44:45], off offset:192
	global_load_dwordx4 v[212:215], v[46:47], off offset:192
	global_load_dwordx4 v[176:179], v[44:45], off offset:224
	global_load_dwordx4 v[216:219], v[46:47], off offset:224
	ds_read_b128 v[220:223], v50 offset:48880
	ds_read_b128 v[224:227], v50 offset:48912
	ds_read_b128 v[232:235], v50 offset:48944
	ds_read_b128 v[236:239], v50 offset:48976
	ds_read_b128 v[240:243], v50 offset:49008
	ds_read_b128 v[244:247], v50 offset:49040
	ds_read_b128 v[40:43], v50 offset:49072
	ds_read_b128 v[36:39], v50 offset:49104
	s_waitcnt vmcnt(15) lgkmcnt(7)
	v_mfma_f32_32x32x16_bf16 v[18:33], v[148:151], v[220:223], 0
	s_waitcnt vmcnt(14)
	v_mfma_f32_32x32x16_bf16 v[2:17], v[180:183], v[220:223], 0
	s_waitcnt vmcnt(13) lgkmcnt(6)
; #define LAS __attribute__((address_space(3)))
; __device__ __forceinline__ unsigned pk2(float lo, float hi) { return f2bf(lo) | (f2bf(hi) << 16); }
; __device__ __forceinline__ float bflo(unsigned w) { return __uint_as_float(w << 16); }
; __device__ __forceinline__ float bfhi(unsigned w) { return __uint_as_float(w & 0xffff0000u); }
; __device__ __forceinline__ float silu(float x) { return x / (1.f + __expf(-x)); }
; __device__ __forceinline__ void pool_item(const Args& A, const Ctx& C0, int l, int row0, int t0, int pos0, const float* hist, float* outpool) {
;     ...
; #pragma unroll
;     for (int ks = 0; ks < 8; ++ks) { const bf16x8 df = *(const LAS bf16x8*)(Dm + tk * PP + g * 128 + ks * 16 + 8 * h);
; #pragma unroll
;         for (int dt = 0; dt < 2; ++dt) { const bf16x8 af = *(const bf16x8*)(PW + (size_t)(ddh * 64 + dt * 32 + tk) * 128 + ks * 16 + 8 * h);
;             acc[dt] = __builtin_amdgcn_mfma_f32_32x32x16_bf16(af, df, acc[dt], 0, 0, 0); }
;     }
;     const size_t row = (size_t)(row0 + tk);
;     const float* psc = A.in[I_POOLS] + l * 512;
; #pragma unroll
;     for (int dt = 0; dt < 2; ++dt)
; #pragma unroll
;         for (int rq = 0; rq < 4; ++rq) { const int cc = g * 128 + ddh * 64 + dt * 32 + 8 * rq + 4 * h;
;             const v2u gx = *(const v2u*)(U + row * DIN + C_GP + cc); const f32x4 sc = *(const f32x4*)(psc + cc);
;             const float o0 = acc[dt][4 * rq] * sc.x * silu(bflo(gx.x)), o1 = acc[dt][4 * rq + 1] * sc.y * silu(bfhi(gx.x)), o2 = acc[dt][4 * rq + 2] * sc.z * silu(bflo(gx.y)), o3 = acc[dt][4 * rq + 3] * sc.w * silu(bfhi(gx.y));
;             v2u o; o.x = pk2(o0, o1); o.y = pk2(o2, o3);
;             *(v2u*)(MIX + row * D + cc) = o; }
	v_mfma_f32_32x32x16_bf16 v[18:33], v[152:155], v[224:227], v[18:33]
	s_waitcnt vmcnt(12)
	v_mfma_f32_32x32x16_bf16 v[2:17], v[188:191], v[224:227], v[2:17]
	s_waitcnt vmcnt(11) lgkmcnt(5)
	v_mfma_f32_32x32x16_bf16 v[18:33], v[156:159], v[232:235], v[18:33]
	s_waitcnt vmcnt(10)
	v_mfma_f32_32x32x16_bf16 v[2:17], v[192:195], v[232:235], v[2:17]
	s_waitcnt vmcnt(9) lgkmcnt(4)
	v_mfma_f32_32x32x16_bf16 v[18:33], v[160:163], v[236:239], v[18:33]
	s_waitcnt vmcnt(8)
	v_mfma_f32_32x32x16_bf16 v[2:17], v[196:199], v[236:239], v[2:17]
	s_waitcnt vmcnt(7) lgkmcnt(3)
	v_mfma_f32_32x32x16_bf16 v[18:33], v[164:167], v[240:243], v[18:33]
	s_waitcnt vmcnt(6)
	v_mfma_f32_32x32x16_bf16 v[2:17], v[200:203], v[240:243], v[2:17]
	s_waitcnt vmcnt(5) lgkmcnt(2)
	v_mfma_f32_32x32x16_bf16 v[18:33], v[168:171], v[244:247], v[18:33]
	s_waitcnt vmcnt(4)
	v_mfma_f32_32x32x16_bf16 v[2:17], v[208:211], v[244:247], v[2:17]
	s_waitcnt vmcnt(3) lgkmcnt(1)
	v_mfma_f32_32x32x16_bf16 v[18:33], v[172:175], v[40:43], v[18:33]
	s_waitcnt vmcnt(2)
	v_mfma_f32_32x32x16_bf16 v[2:17], v[212:215], v[40:43], v[2:17]
	s_waitcnt vmcnt(1) lgkmcnt(0)
	v_mfma_f32_32x32x16_bf16 v[18:33], v[176:179], v[36:39], v[18:33]
	s_nop 11
	v_mov_b32_e32 v52, v18
	v_mov_b32_e32 v53, v20
	s_waitcnt vmcnt(0)
	v_mfma_f32_32x32x16_bf16 v[2:17], v[216:219], v[36:39], v[2:17]
	v_lshl_or_b32 v36, v48, 2, s0
	v_mov_b64_e32 v[38:39], s[62:63]
	s_movk_i32 s0, 0x2b00
	v_ashrrev_i32_e32 v37, 31, v36
	v_mad_u64_u32 v[38:39], s[0:1], v0, s0, v[38:39]
	v_lshlrev_b64 v[46:47], 1, v[36:37]
	v_lshl_add_u64 v[38:39], v[38:39], 0, v[46:47]
	flat_load_dwordx2 v[48:49], v[38:39] offset:1024
	v_lshlrev_b64 v[40:41], 12, v[0:1]
	v_lshl_add_u64 v[36:37], v[36:37], 2, s[78:79]
	v_lshl_add_u64 v[44:45], s[24:25], 0, v[40:41]
	global_load_dwordx4 v[40:43], v[36:37], off
	s_waitcnt vmcnt(0) lgkmcnt(0)
	v_lshlrev_b32_e32 v0, 16, v49
	v_lshlrev_b32_e32 v56, 16, v48
	v_mul_f32_e32 v50, 0xbfb8aa3b, v56
	v_mul_f32_e32 v18, 0xbfb8aa3b, v0
	v_exp_f32_e32 v50, v50
	v_exp_f32_e32 v51, v18
	v_mov_b32_e32 v54, v40
	v_mov_b32_e32 v55, v42
	v_and_b32_e32 v57, 0xffff0000, v49
	v_pk_add_f32 v[50:51], v[50:51], 1.0 op_sel_hi:[1,0]
	v_and_b32_e32 v58, 0xffff0000, v48
	v_div_scale_f32 v18, s[0:1], v51, v51, v0
	v_rcp_f32_e32 v20, v18
	v_mul_f32_e32 v48, 0xbfb8aa3b, v58
	v_exp_f32_e32 v48, v48
	v_pk_mul_f32 v[52:53], v[52:53], v[54:55]
	v_fma_f32 v40, -v18, v20, 1.0
	v_fmac_f32_e32 v20, v40, v20
	v_div_scale_f32 v40, vcc, v0, v51, v0
	v_mul_f32_e32 v42, v40, v20
	v_fma_f32 v49, -v18, v42, v40
	v_fmac_f32_e32 v42, v49, v20
	v_fma_f32 v18, -v18, v42, v40
	v_div_fmas_f32 v18, v18, v20, v42
	v_div_fixup_f32 v51, v18, v51, v0
	v_div_scale_f32 v0, s[0:1], v50, v50, v56
	v_rcp_f32_e32 v18, v0
	s_nop 0
	v_fma_f32 v20, -v0, v18, 1.0
	v_fmac_f32_e32 v18, v20, v18
	v_div_scale_f32 v20, vcc, v56, v50, v56
	v_mul_f32_e32 v40, v20, v18
	v_fma_f32 v42, -v0, v40, v20
	v_fmac_f32_e32 v40, v42, v18
	v_fma_f32 v0, -v0, v40, v20
	v_div_fmas_f32 v0, v0, v18, v40
	v_div_fixup_f32 v50, v0, v50, v56
	v_mul_f32_e32 v0, 0xbfb8aa3b, v57
	v_exp_f32_e32 v49, v0
	v_mov_b32_e32 v20, v19
	v_mov_b32_e32 v42, v41
	v_pk_mul_f32 v[18:19], v[20:21], v[42:43]
	v_pk_add_f32 v[20:21], v[48:49], 1.0 op_sel_hi:[1,0]
	v_pk_mul_f32 v[50:51], v[52:53], v[50:51]
	v_div_scale_f32 v0, s[0:1], v21, v21, v57
	v_rcp_f32_e32 v40, v0
	s_nop 0
	v_fma_f32 v41, -v0, v40, 1.0
	v_fmac_f32_e32 v40, v41, v40
	v_div_scale_f32 v41, vcc, v57, v21, v57
	v_mul_f32_e32 v42, v41, v40
	v_fma_f32 v43, -v0, v42, v41
	v_fmac_f32_e32 v42, v43, v40
	v_fma_f32 v0, -v0, v42, v41
	v_div_fmas_f32 v0, v0, v40, v42
	v_div_fixup_f32 v21, v0, v21, v57
	v_div_scale_f32 v0, s[0:1], v20, v20, v58
	v_rcp_f32_e32 v40, v0
	s_mov_b64 s[0:1], 0x7b27900
	v_fma_f32 v41, -v0, v40, 1.0
	v_fmac_f32_e32 v40, v41, v40
	v_div_scale_f32 v41, vcc, v58, v20, v58
	v_mul_f32_e32 v42, v41, v40
	v_fma_f32 v43, -v0, v42, v41
	v_fmac_f32_e32 v42, v43, v40
	v_fma_f32 v0, -v0, v42, v41
	v_div_fmas_f32 v0, v0, v40, v42
	v_div_fixup_f32 v20, v0, v20, v58
	v_pk_mul_f32 v[18:19], v[18:19], v[20:21]
	v_and_b32_sdwa v0, v51, v252 dst_sel:DWORD dst_unused:UNUSED_PAD src0_sel:WORD_1 src1_sel:DWORD
	v_and_b32_sdwa v21, v19, v252 dst_sel:DWORD dst_unused:UNUSED_PAD src0_sel:WORD_1 src1_sel:DWORD
	v_and_b32_sdwa v40, v18, v252 dst_sel:DWORD dst_unused:UNUSED_PAD src0_sel:WORD_1 src1_sel:DWORD
	v_and_b32_sdwa v20, v50, v252 dst_sel:DWORD dst_unused:UNUSED_PAD src0_sel:WORD_1 src1_sel:DWORD
	v_add3_u32 v19, v19, v21, s33
	v_add3_u32 v18, v18, v40, s33
	v_add3_u32 v20, v50, v20, s33
	v_add3_u32 v0, v51, v0, s33
	v_and_b32_e32 v19, 0xffff0000, v19
	v_and_b32_e32 v18, 0xffff0000, v18
	v_lshl_add_u64 v[40:41], v[44:45], 0, v[46:47]
	v_or_b32_sdwa v21, v19, v0 dst_sel:DWORD dst_unused:UNUSED_PAD src0_sel:DWORD src1_sel:WORD_1
	v_or_b32_sdwa v20, v18, v20 dst_sel:DWORD dst_unused:UNUSED_PAD src0_sel:DWORD src1_sel:WORD_1
	v_lshl_add_u64 v[18:19], v[40:41], 0, s[0:1]
	s_mov_b32 s0, 0x7b27000
	v_add_co_u32_e32 v40, vcc, s0, v40
	v_mov_b32_e32 v46, v22
	s_nop 0
	v_addc_co_u32_e32 v41, vcc, 0, v41, vcc
	flat_store_dwordx2 v[40:41], v[20:21] offset:2304
	flat_load_dwordx2 v[20:21], v[38:39] offset:1040
	s_nop 0
	global_load_dwordx4 v[40:43], v[36:37], off offset:32
	v_mov_b32_e32 v47, v24
	s_waitcnt vmcnt(0) lgkmcnt(0)
; __device__ __forceinline__ unsigned pk2(float lo, float hi) { return f2bf(lo) | (f2bf(hi) << 16); }
; __device__ __forceinline__ float bflo(unsigned w) { return __uint_as_float(w << 16); }
; __device__ __forceinline__ float bfhi(unsigned w) { return __uint_as_float(w & 0xffff0000u); }
; __device__ __forceinline__ float silu(float x) { return x / (1.f + __expf(-x)); }
; __device__ __forceinline__ void pool_item(const Args& A, const Ctx& C0, int l, int row0, int t0, int pos0, const float* hist, float* outpool) {
;     ...
; #pragma unroll
;     for (int dt = 0; dt < 2; ++dt)
; #pragma unroll
;         for (int rq = 0; rq < 4; ++rq) { const int cc = g * 128 + ddh * 64 + dt * 32 + 8 * rq + 4 * h;
;             const v2u gx = *(const v2u*)(U + row * DIN + C_GP + cc); const f32x4 sc = *(const f32x4*)(psc + cc);
;             const float o0 = acc[dt][4 * rq] * sc.x * silu(bflo(gx.x)), o1 = acc[dt][4 * rq + 1] * sc.y * silu(bfhi(gx.x)), o2 = acc[dt][4 * rq + 2] * sc.z * silu(bflo(gx.y)), o3 = acc[dt][4 * rq + 3] * sc.w * silu(bfhi(gx.y));
;             v2u o; o.x = pk2(o0, o1); o.y = pk2(o2, o3);
;             *(v2u*)(MIX + row * D + cc) = o; }
	v_lshlrev_b32_e32 v0, 16, v21
	v_lshlrev_b32_e32 v50, 16, v20
	v_mul_f32_e32 v44, 0xbfb8aa3b, v50
	v_and_b32_e32 v51, 0xffff0000, v21
	v_mul_f32_e32 v21, 0xbfb8aa3b, v0
	v_exp_f32_e32 v44, v44
	v_exp_f32_e32 v45, v21
	v_mov_b32_e32 v48, v40
	v_mov_b32_e32 v49, v42
	v_and_b32_e32 v52, 0xffff0000, v20
	v_pk_add_f32 v[44:45], v[44:45], 1.0 op_sel_hi:[1,0]
	v_mul_f32_e32 v20, 0xbfb8aa3b, v52
	v_div_scale_f32 v21, s[0:1], v45, v45, v0
	v_rcp_f32_e32 v22, v21
	v_exp_f32_e32 v20, v20
	v_pk_mul_f32 v[46:47], v[46:47], v[48:49]
	v_fma_f32 v24, -v21, v22, 1.0
	v_fmac_f32_e32 v22, v24, v22
	v_div_scale_f32 v24, vcc, v0, v45, v0
	v_mul_f32_e32 v40, v24, v22
	v_fma_f32 v42, -v21, v40, v24
	v_fmac_f32_e32 v40, v42, v22
	v_fma_f32 v21, -v21, v40, v24
	v_div_fmas_f32 v21, v21, v22, v40
	v_div_fixup_f32 v45, v21, v45, v0
	v_div_scale_f32 v0, s[0:1], v44, v44, v50
	v_rcp_f32_e32 v21, v0
	v_mov_b32_e32 v42, v41
	v_fma_f32 v22, -v0, v21, 1.0
	v_fmac_f32_e32 v21, v22, v21
	v_div_scale_f32 v22, vcc, v50, v44, v50
	v_mul_f32_e32 v24, v22, v21
	v_fma_f32 v40, -v0, v24, v22
	v_fmac_f32_e32 v24, v40, v21
	v_fma_f32 v0, -v0, v24, v22
	v_div_fmas_f32 v0, v0, v21, v24
	v_div_fixup_f32 v44, v0, v44, v50
	v_mul_f32_e32 v0, 0xbfb8aa3b, v51
	v_exp_f32_e32 v21, v0
	v_mov_b32_e32 v24, v23
	v_pk_mul_f32 v[22:23], v[24:25], v[42:43]
	v_pk_mul_f32 v[44:45], v[46:47], v[44:45]
	v_pk_add_f32 v[20:21], v[20:21], 1.0 op_sel_hi:[1,0]
	v_mov_b32_e32 v42, v26
	v_div_scale_f32 v0, s[0:1], v21, v21, v51
	v_rcp_f32_e32 v24, v0
	v_mov_b32_e32 v43, v28
	v_fma_f32 v25, -v0, v24, 1.0
	v_fmac_f32_e32 v24, v25, v24
	v_div_scale_f32 v25, vcc, v51, v21, v51
	v_mul_f32_e32 v40, v25, v24
	v_fma_f32 v41, -v0, v40, v25
	v_fmac_f32_e32 v40, v41, v24
	v_fma_f32 v0, -v0, v40, v25
	v_div_fmas_f32 v0, v0, v24, v40
	v_div_fixup_f32 v21, v0, v21, v51
	v_div_scale_f32 v0, s[0:1], v20, v20, v52
	v_rcp_f32_e32 v24, v0
	s_nop 0
	v_fma_f32 v25, -v0, v24, 1.0
	v_fmac_f32_e32 v24, v25, v24
	v_div_scale_f32 v25, vcc, v52, v20, v52
	v_mul_f32_e32 v40, v25, v24
	v_fma_f32 v41, -v0, v40, v25
	v_fmac_f32_e32 v40, v41, v24
	v_fma_f32 v0, -v0, v40, v25
	v_div_fmas_f32 v0, v0, v24, v40
	v_div_fixup_f32 v20, v0, v20, v52
	v_pk_mul_f32 v[20:21], v[22:23], v[20:21]
	v_and_b32_sdwa v0, v45, v252 dst_sel:DWORD dst_unused:UNUSED_PAD src0_sel:WORD_1 src1_sel:DWORD
	v_and_b32_sdwa v23, v21, v252 dst_sel:DWORD dst_unused:UNUSED_PAD src0_sel:WORD_1 src1_sel:DWORD
	v_and_b32_sdwa v24, v20, v252 dst_sel:DWORD dst_unused:UNUSED_PAD src0_sel:WORD_1 src1_sel:DWORD
	v_and_b32_sdwa v22, v44, v252 dst_sel:DWORD dst_unused:UNUSED_PAD src0_sel:WORD_1 src1_sel:DWORD
	v_add3_u32 v21, v21, v23, s33
	v_add3_u32 v20, v20, v24, s33
	v_add3_u32 v22, v44, v22, s33
	v_add3_u32 v0, v45, v0, s33
	v_and_b32_e32 v21, 0xffff0000, v21
	v_and_b32_e32 v20, 0xffff0000, v20
	v_or_b32_sdwa v21, v21, v0 dst_sel:DWORD dst_unused:UNUSED_PAD src0_sel:DWORD src1_sel:WORD_1
	v_or_b32_sdwa v20, v20, v22 dst_sel:DWORD dst_unused:UNUSED_PAD src0_sel:DWORD src1_sel:WORD_1
	flat_store_dwordx2 v[18:19], v[20:21] offset:16
	flat_load_dwordx2 v[24:25], v[38:39] offset:1056
	s_nop 0
	global_load_dwordx4 v[20:23], v[36:37], off offset:64
	s_waitcnt vmcnt(0) lgkmcnt(0)
	v_lshlrev_b32_e32 v0, 16, v25
	v_lshlrev_b32_e32 v46, 16, v24
	v_mul_f32_e32 v40, 0xbfb8aa3b, v46
	v_mov_b32_e32 v44, v20
	v_mul_f32_e32 v20, 0xbfb8aa3b, v0
	v_exp_f32_e32 v40, v40
	v_exp_f32_e32 v41, v20
	v_mov_b32_e32 v45, v22
	v_and_b32_e32 v47, 0xffff0000, v25
	v_and_b32_e32 v48, 0xffff0000, v24
	v_pk_add_f32 v[40:41], v[40:41], 1.0 op_sel_hi:[1,0]
	v_mul_f32_e32 v24, 0xbfb8aa3b, v48
	v_div_scale_f32 v20, s[0:1], v41, v41, v0
	v_rcp_f32_e32 v22, v20
	v_exp_f32_e32 v24, v24
	v_pk_mul_f32 v[42:43], v[42:43], v[44:45]
	v_fma_f32 v25, -v20, v22, 1.0
	v_fmac_f32_e32 v22, v25, v22
	v_div_scale_f32 v25, vcc, v0, v41, v0
	v_mul_f32_e32 v26, v25, v22
	v_fma_f32 v28, -v20, v26, v25
	v_fmac_f32_e32 v26, v28, v22
	v_fma_f32 v20, -v20, v26, v25
	v_div_fmas_f32 v20, v20, v22, v26
	v_div_fixup_f32 v41, v20, v41, v0
	v_div_scale_f32 v0, s[0:1], v40, v40, v46
	v_rcp_f32_e32 v20, v0
	v_mov_b32_e32 v28, v27
	v_fma_f32 v22, -v0, v20, 1.0
	v_fmac_f32_e32 v20, v22, v20
	v_div_scale_f32 v22, vcc, v46, v40, v46
	v_mul_f32_e32 v25, v22, v20
	v_fma_f32 v26, -v0, v25, v22
	v_fmac_f32_e32 v25, v26, v20
	v_fma_f32 v0, -v0, v25, v22
	v_div_fmas_f32 v0, v0, v20, v25
	v_div_fixup_f32 v40, v0, v40, v46
	v_mul_f32_e32 v0, 0xbfb8aa3b, v47
	v_exp_f32_e32 v25, v0
	v_mov_b32_e32 v22, v21
	v_pk_mul_f32 v[20:21], v[28:29], v[22:23]
	v_pk_mul_f32 v[40:41], v[42:43], v[40:41]
	v_pk_add_f32 v[22:23], v[24:25], 1.0 op_sel_hi:[1,0]
	v_mov_b32_e32 v28, v30
	v_div_scale_f32 v0, s[0:1], v23, v23, v47
	v_rcp_f32_e32 v24, v0
	v_mov_b32_e32 v29, v32
	v_fma_f32 v25, -v0, v24, 1.0
	v_fmac_f32_e32 v24, v25, v24
	v_div_scale_f32 v25, vcc, v47, v23, v47
	v_mul_f32_e32 v26, v25, v24
	v_fma_f32 v27, -v0, v26, v25
	v_fmac_f32_e32 v26, v27, v24
	v_fma_f32 v0, -v0, v26, v25
	v_div_fmas_f32 v0, v0, v24, v26
	v_div_fixup_f32 v23, v0, v23, v47
	v_div_scale_f32 v0, s[0:1], v22, v22, v48
	v_rcp_f32_e32 v24, v0
	s_nop 0
	v_fma_f32 v25, -v0, v24, 1.0
	v_fmac_f32_e32 v24, v25, v24
	v_div_scale_f32 v25, vcc, v48, v22, v48
	v_mul_f32_e32 v26, v25, v24
	v_fma_f32 v27, -v0, v26, v25
	v_fmac_f32_e32 v26, v27, v24
	v_fma_f32 v0, -v0, v26, v25
	v_div_fmas_f32 v0, v0, v24, v26
	v_div_fixup_f32 v22, v0, v22, v48
	v_pk_mul_f32 v[20:21], v[20:21], v[22:23]
	v_and_b32_sdwa v0, v41, v252 dst_sel:DWORD dst_unused:UNUSED_PAD src0_sel:WORD_1 src1_sel:DWORD
	v_and_b32_sdwa v23, v21, v252 dst_sel:DWORD dst_unused:UNUSED_PAD src0_sel:WORD_1 src1_sel:DWORD
	v_and_b32_sdwa v24, v20, v252 dst_sel:DWORD dst_unused:UNUSED_PAD src0_sel:WORD_1 src1_sel:DWORD
	v_and_b32_sdwa v22, v40, v252 dst_sel:DWORD dst_unused:UNUSED_PAD src0_sel:WORD_1 src1_sel:DWORD
	v_add3_u32 v21, v21, v23, s33
	v_add3_u32 v20, v20, v24, s33
	v_add3_u32 v22, v40, v22, s33
	v_add3_u32 v0, v41, v0, s33
	v_and_b32_e32 v21, 0xffff0000, v21
	v_and_b32_e32 v20, 0xffff0000, v20
	v_or_b32_sdwa v21, v21, v0 dst_sel:DWORD dst_unused:UNUSED_PAD src0_sel:DWORD src1_sel:WORD_1
	v_or_b32_sdwa v20, v20, v22 dst_sel:DWORD dst_unused:UNUSED_PAD src0_sel:DWORD src1_sel:WORD_1
	flat_store_dwordx2 v[18:19], v[20:21] offset:32
	flat_load_dwordx2 v[20:21], v[38:39] offset:1072
	s_nop 0
	global_load_dwordx4 v[22:25], v[36:37], off offset:96
	s_waitcnt vmcnt(0) lgkmcnt(0)
; __device__ __forceinline__ unsigned pk2(float lo, float hi) { return f2bf(lo) | (f2bf(hi) << 16); }
; __device__ __forceinline__ float bflo(unsigned w) { return __uint_as_float(w << 16); }
; __device__ __forceinline__ float bfhi(unsigned w) { return __uint_as_float(w & 0xffff0000u); }
; __device__ __forceinline__ float silu(float x) { return x / (1.f + __expf(-x)); }
; __device__ __forceinline__ void pool_item(const Args& A, const Ctx& C0, int l, int row0, int t0, int pos0, const float* hist, float* outpool) {
;     ...
; #pragma unroll
;     for (int dt = 0; dt < 2; ++dt)
; #pragma unroll
;         for (int rq = 0; rq < 4; ++rq) { const int cc = g * 128 + ddh * 64 + dt * 32 + 8 * rq + 4 * h;
;             const v2u gx = *(const v2u*)(U + row * DIN + C_GP + cc); const f32x4 sc = *(const f32x4*)(psc + cc);
;             const float o0 = acc[dt][4 * rq] * sc.x * silu(bflo(gx.x)), o1 = acc[dt][4 * rq + 1] * sc.y * silu(bfhi(gx.x)), o2 = acc[dt][4 * rq + 2] * sc.z * silu(bflo(gx.y)), o3 = acc[dt][4 * rq + 3] * sc.w * silu(bfhi(gx.y));
;             v2u o; o.x = pk2(o0, o1); o.y = pk2(o2, o3);
;             *(v2u*)(MIX + row * D + cc) = o; }
	v_lshlrev_b32_e32 v0, 16, v21
	v_lshlrev_b32_e32 v42, 16, v20
	v_mul_f32_e32 v26, 0xbfb8aa3b, v42
	v_and_b32_e32 v43, 0xffff0000, v21
	v_mul_f32_e32 v21, 0xbfb8aa3b, v0
	v_exp_f32_e32 v26, v26
	v_exp_f32_e32 v27, v21
	v_mov_b32_e32 v40, v22
	v_mov_b32_e32 v41, v24
	v_and_b32_e32 v44, 0xffff0000, v20
	v_pk_add_f32 v[26:27], v[26:27], 1.0 op_sel_hi:[1,0]
	v_mul_f32_e32 v20, 0xbfb8aa3b, v44
	v_div_scale_f32 v21, s[0:1], v27, v27, v0
	v_rcp_f32_e32 v22, v21
	v_exp_f32_e32 v20, v20
	v_pk_mul_f32 v[28:29], v[28:29], v[40:41]
	v_fma_f32 v24, -v21, v22, 1.0
	v_fmac_f32_e32 v22, v24, v22
	v_div_scale_f32 v24, vcc, v0, v27, v0
	v_mul_f32_e32 v30, v24, v22
	v_fma_f32 v32, -v21, v30, v24
	v_fmac_f32_e32 v30, v32, v22
	v_fma_f32 v21, -v21, v30, v24
	v_div_fmas_f32 v21, v21, v22, v30
	v_div_fixup_f32 v27, v21, v27, v0
	v_div_scale_f32 v0, s[0:1], v26, v26, v42
	v_rcp_f32_e32 v21, v0
	v_mov_b32_e32 v32, v31
	v_fma_f32 v22, -v0, v21, 1.0
	v_fmac_f32_e32 v21, v22, v21
	v_div_scale_f32 v22, vcc, v42, v26, v42
	v_mul_f32_e32 v24, v22, v21
	v_fma_f32 v30, -v0, v24, v22
	v_fmac_f32_e32 v24, v30, v21
	v_fma_f32 v0, -v0, v24, v22
	v_div_fmas_f32 v0, v0, v21, v24
	v_div_fixup_f32 v26, v0, v26, v42
	v_mul_f32_e32 v0, 0xbfb8aa3b, v43
	v_exp_f32_e32 v21, v0
	v_mov_b32_e32 v24, v23
	v_pk_mul_f32 v[22:23], v[32:33], v[24:25]
	v_pk_mul_f32 v[26:27], v[28:29], v[26:27]
	v_pk_add_f32 v[20:21], v[20:21], 1.0 op_sel_hi:[1,0]
	s_nop 0
	v_div_scale_f32 v0, s[0:1], v21, v21, v43
	v_rcp_f32_e32 v24, v0
	s_nop 0
	v_fma_f32 v25, -v0, v24, 1.0
	v_fmac_f32_e32 v24, v25, v24
	v_div_scale_f32 v25, vcc, v43, v21, v43
	v_mul_f32_e32 v28, v25, v24
	v_fma_f32 v29, -v0, v28, v25
	v_fmac_f32_e32 v28, v29, v24
	v_fma_f32 v0, -v0, v28, v25
	v_div_fmas_f32 v0, v0, v24, v28
	v_div_fixup_f32 v21, v0, v21, v43
	v_div_scale_f32 v0, s[0:1], v20, v20, v44
	v_rcp_f32_e32 v24, v0
	s_nop 0
	v_fma_f32 v25, -v0, v24, 1.0
	v_fmac_f32_e32 v24, v25, v24
	v_div_scale_f32 v25, vcc, v44, v20, v44
	v_mul_f32_e32 v28, v25, v24
	v_fma_f32 v29, -v0, v28, v25
	v_fmac_f32_e32 v28, v29, v24
	v_fma_f32 v0, -v0, v28, v25
	v_div_fmas_f32 v0, v0, v24, v28
	v_div_fixup_f32 v20, v0, v20, v44
	v_pk_mul_f32 v[20:21], v[22:23], v[20:21]
	v_and_b32_sdwa v0, v27, v252 dst_sel:DWORD dst_unused:UNUSED_PAD src0_sel:WORD_1 src1_sel:DWORD
	v_and_b32_sdwa v23, v21, v252 dst_sel:DWORD dst_unused:UNUSED_PAD src0_sel:WORD_1 src1_sel:DWORD
	v_and_b32_sdwa v24, v20, v252 dst_sel:DWORD dst_unused:UNUSED_PAD src0_sel:WORD_1 src1_sel:DWORD
	v_and_b32_sdwa v22, v26, v252 dst_sel:DWORD dst_unused:UNUSED_PAD src0_sel:WORD_1 src1_sel:DWORD
	v_add3_u32 v21, v21, v23, s33
	v_add3_u32 v20, v20, v24, s33
	v_add3_u32 v22, v26, v22, s33
	v_add3_u32 v0, v27, v0, s33
	v_and_b32_e32 v21, 0xffff0000, v21
	v_and_b32_e32 v20, 0xffff0000, v20
	v_or_b32_sdwa v21, v21, v0 dst_sel:DWORD dst_unused:UNUSED_PAD src0_sel:DWORD src1_sel:WORD_1
	v_or_b32_sdwa v20, v20, v22 dst_sel:DWORD dst_unused:UNUSED_PAD src0_sel:DWORD src1_sel:WORD_1
	flat_store_dwordx2 v[18:19], v[20:21] offset:48
	flat_load_dwordx2 v[20:21], v[38:39] offset:1088
	s_nop 0
	global_load_dwordx4 v[22:25], v[36:37], off offset:128
	v_mov_b32_e32 v28, v2
	v_mov_b32_e32 v29, v4
	s_waitcnt vmcnt(0) lgkmcnt(0)
	v_lshlrev_b32_e32 v0, 16, v21
	v_lshlrev_b32_e32 v32, 16, v20
	v_mul_f32_e32 v26, 0xbfb8aa3b, v32
	v_mul_f32_e32 v2, 0xbfb8aa3b, v0
	v_exp_f32_e32 v26, v26
	v_exp_f32_e32 v27, v2
	v_and_b32_e32 v33, 0xffff0000, v21
	v_mov_b32_e32 v30, v22
	v_mov_b32_e32 v31, v24
	v_pk_add_f32 v[26:27], v[26:27], 1.0 op_sel_hi:[1,0]
	v_and_b32_e32 v40, 0xffff0000, v20
	v_div_scale_f32 v2, s[0:1], v27, v27, v0
	v_rcp_f32_e32 v4, v2
	v_mul_f32_e32 v20, 0xbfb8aa3b, v40
	v_exp_f32_e32 v20, v20
	v_pk_mul_f32 v[28:29], v[28:29], v[30:31]
	v_fma_f32 v21, -v2, v4, 1.0
	v_fmac_f32_e32 v4, v21, v4
	v_div_scale_f32 v21, vcc, v0, v27, v0
	v_mul_f32_e32 v22, v21, v4
	v_fma_f32 v24, -v2, v22, v21
	v_fmac_f32_e32 v22, v24, v4
	v_fma_f32 v2, -v2, v22, v21
	v_div_fmas_f32 v2, v2, v4, v22
	v_div_fixup_f32 v27, v2, v27, v0
	v_div_scale_f32 v0, s[0:1], v26, v26, v32
	v_rcp_f32_e32 v2, v0
	v_mov_b32_e32 v24, v23
	v_fma_f32 v4, -v0, v2, 1.0
	v_fmac_f32_e32 v2, v4, v2
	v_div_scale_f32 v4, vcc, v32, v26, v32
	v_mul_f32_e32 v21, v4, v2
	v_fma_f32 v22, -v0, v21, v4
	v_fmac_f32_e32 v21, v22, v2
	v_fma_f32 v0, -v0, v21, v4
	v_div_fmas_f32 v0, v0, v2, v21
	v_div_fixup_f32 v26, v0, v26, v32
	v_mul_f32_e32 v0, 0xbfb8aa3b, v33
	v_exp_f32_e32 v21, v0
	v_mov_b32_e32 v4, v3
	v_pk_mul_f32 v[2:3], v[4:5], v[24:25]
	v_pk_mul_f32 v[26:27], v[28:29], v[26:27]
	v_pk_add_f32 v[4:5], v[20:21], 1.0 op_sel_hi:[1,0]
	v_mov_b32_e32 v24, v6
	v_div_scale_f32 v0, s[0:1], v5, v5, v33
	v_rcp_f32_e32 v20, v0
	v_mov_b32_e32 v25, v8
	v_fma_f32 v21, -v0, v20, 1.0
	v_fmac_f32_e32 v20, v21, v20
	v_div_scale_f32 v21, vcc, v33, v5, v33
	v_mul_f32_e32 v22, v21, v20
	v_fma_f32 v23, -v0, v22, v21
	v_fmac_f32_e32 v22, v23, v20
	v_fma_f32 v0, -v0, v22, v21
	v_div_fmas_f32 v0, v0, v20, v22
	v_div_fixup_f32 v5, v0, v5, v33
	v_div_scale_f32 v0, s[0:1], v4, v4, v40
	v_rcp_f32_e32 v20, v0
	s_nop 0
	v_fma_f32 v21, -v0, v20, 1.0
	v_fmac_f32_e32 v20, v21, v20
	v_div_scale_f32 v21, vcc, v40, v4, v40
	v_mul_f32_e32 v22, v21, v20
	v_fma_f32 v23, -v0, v22, v21
	v_fmac_f32_e32 v22, v23, v20
	v_fma_f32 v0, -v0, v22, v21
	v_div_fmas_f32 v0, v0, v20, v22
	v_div_fixup_f32 v4, v0, v4, v40
	v_pk_mul_f32 v[2:3], v[2:3], v[4:5]
	v_and_b32_sdwa v0, v27, v252 dst_sel:DWORD dst_unused:UNUSED_PAD src0_sel:WORD_1 src1_sel:DWORD
	v_and_b32_sdwa v5, v3, v252 dst_sel:DWORD dst_unused:UNUSED_PAD src0_sel:WORD_1 src1_sel:DWORD
	v_and_b32_sdwa v20, v2, v252 dst_sel:DWORD dst_unused:UNUSED_PAD src0_sel:WORD_1 src1_sel:DWORD
	v_and_b32_sdwa v4, v26, v252 dst_sel:DWORD dst_unused:UNUSED_PAD src0_sel:WORD_1 src1_sel:DWORD
	v_add3_u32 v3, v3, v5, s33
	v_add3_u32 v2, v2, v20, s33
	v_add3_u32 v4, v26, v4, s33
	v_add3_u32 v0, v27, v0, s33
	v_and_b32_e32 v3, 0xffff0000, v3
	v_and_b32_e32 v2, 0xffff0000, v2
	v_or_b32_sdwa v3, v3, v0 dst_sel:DWORD dst_unused:UNUSED_PAD src0_sel:DWORD src1_sel:WORD_1
	v_or_b32_sdwa v2, v2, v4 dst_sel:DWORD dst_unused:UNUSED_PAD src0_sel:DWORD src1_sel:WORD_1
	flat_store_dwordx2 v[18:19], v[2:3] offset:64
	flat_load_dwordx2 v[20:21], v[38:39] offset:1104
	s_nop 0
	global_load_dwordx4 v[2:5], v[36:37], off offset:160
	s_waitcnt vmcnt(0) lgkmcnt(0)
; __device__ __forceinline__ unsigned pk2(float lo, float hi) { return f2bf(lo) | (f2bf(hi) << 16); }
; __device__ __forceinline__ float bflo(unsigned w) { return __uint_as_float(w << 16); }
; __device__ __forceinline__ float bfhi(unsigned w) { return __uint_as_float(w & 0xffff0000u); }
; __device__ __forceinline__ float silu(float x) { return x / (1.f + __expf(-x)); }
; __device__ __forceinline__ void pool_item(const Args& A, const Ctx& C0, int l, int row0, int t0, int pos0, const float* hist, float* outpool) {
;     ...
; #pragma unroll
;     for (int dt = 0; dt < 2; ++dt)
; #pragma unroll
;         for (int rq = 0; rq < 4; ++rq) { const int cc = g * 128 + ddh * 64 + dt * 32 + 8 * rq + 4 * h;
;             const v2u gx = *(const v2u*)(U + row * DIN + C_GP + cc); const f32x4 sc = *(const f32x4*)(psc + cc);
;             const float o0 = acc[dt][4 * rq] * sc.x * silu(bflo(gx.x)), o1 = acc[dt][4 * rq + 1] * sc.y * silu(bfhi(gx.x)), o2 = acc[dt][4 * rq + 2] * sc.z * silu(bflo(gx.y)), o3 = acc[dt][4 * rq + 3] * sc.w * silu(bfhi(gx.y));
;             v2u o; o.x = pk2(o0, o1); o.y = pk2(o2, o3);
;             *(v2u*)(MIX + row * D + cc) = o; }
	v_lshlrev_b32_e32 v0, 16, v21
	v_lshlrev_b32_e32 v28, 16, v20
	v_mul_f32_e32 v22, 0xbfb8aa3b, v28
	v_mov_b32_e32 v26, v2
	v_mul_f32_e32 v2, 0xbfb8aa3b, v0
	v_exp_f32_e32 v22, v22
	v_exp_f32_e32 v23, v2
	v_mov_b32_e32 v27, v4
	v_and_b32_e32 v29, 0xffff0000, v21
	v_and_b32_e32 v30, 0xffff0000, v20
	v_pk_add_f32 v[22:23], v[22:23], 1.0 op_sel_hi:[1,0]
	v_mul_f32_e32 v20, 0xbfb8aa3b, v30
	v_div_scale_f32 v2, s[0:1], v23, v23, v0
	v_rcp_f32_e32 v4, v2
	v_exp_f32_e32 v20, v20
	v_pk_mul_f32 v[24:25], v[24:25], v[26:27]
	v_fma_f32 v6, -v2, v4, 1.0
	v_fmac_f32_e32 v4, v6, v4
	v_div_scale_f32 v6, vcc, v0, v23, v0
	v_mul_f32_e32 v8, v6, v4
	v_fma_f32 v21, -v2, v8, v6
	v_fmac_f32_e32 v8, v21, v4
	v_fma_f32 v2, -v2, v8, v6
	v_div_fmas_f32 v2, v2, v4, v8
	v_div_fixup_f32 v23, v2, v23, v0
	v_div_scale_f32 v0, s[0:1], v22, v22, v28
	v_rcp_f32_e32 v2, v0
	s_nop 0
	v_fma_f32 v4, -v0, v2, 1.0
	v_fmac_f32_e32 v2, v4, v2
	v_div_scale_f32 v4, vcc, v28, v22, v28
	v_mul_f32_e32 v6, v4, v2
	v_fma_f32 v8, -v0, v6, v4
	v_fmac_f32_e32 v6, v8, v2
	v_fma_f32 v0, -v0, v6, v4
	v_div_fmas_f32 v0, v0, v2, v6
	v_div_fixup_f32 v22, v0, v22, v28
	v_mul_f32_e32 v0, 0xbfb8aa3b, v29
	v_exp_f32_e32 v21, v0
	v_mov_b32_e32 v8, v7
	v_mov_b32_e32 v4, v3
	v_pk_mul_f32 v[2:3], v[8:9], v[4:5]
	v_pk_add_f32 v[4:5], v[20:21], 1.0 op_sel_hi:[1,0]
	v_pk_mul_f32 v[22:23], v[24:25], v[22:23]
	v_div_scale_f32 v0, s[0:1], v5, v5, v29
	v_rcp_f32_e32 v6, v0
	v_mov_b32_e32 v20, v10
	v_mov_b32_e32 v21, v12
	v_fma_f32 v7, -v0, v6, 1.0
	v_fmac_f32_e32 v6, v7, v6
	v_div_scale_f32 v7, vcc, v29, v5, v29
	v_mul_f32_e32 v8, v7, v6
	v_fma_f32 v9, -v0, v8, v7
	v_fmac_f32_e32 v8, v9, v6
	v_fma_f32 v0, -v0, v8, v7
	v_div_fmas_f32 v0, v0, v6, v8
	v_div_fixup_f32 v5, v0, v5, v29
	v_div_scale_f32 v0, s[0:1], v4, v4, v30
	v_rcp_f32_e32 v6, v0
	s_nop 0
	v_fma_f32 v7, -v0, v6, 1.0
	v_fmac_f32_e32 v6, v7, v6
	v_div_scale_f32 v7, vcc, v30, v4, v30
	v_mul_f32_e32 v8, v7, v6
	v_fma_f32 v9, -v0, v8, v7
	v_fmac_f32_e32 v8, v9, v6
	v_fma_f32 v0, -v0, v8, v7
	v_div_fmas_f32 v0, v0, v6, v8
	v_div_fixup_f32 v4, v0, v4, v30
	v_pk_mul_f32 v[2:3], v[2:3], v[4:5]
	v_and_b32_sdwa v0, v23, v252 dst_sel:DWORD dst_unused:UNUSED_PAD src0_sel:WORD_1 src1_sel:DWORD
	v_and_b32_sdwa v5, v3, v252 dst_sel:DWORD dst_unused:UNUSED_PAD src0_sel:WORD_1 src1_sel:DWORD
	v_and_b32_sdwa v6, v2, v252 dst_sel:DWORD dst_unused:UNUSED_PAD src0_sel:WORD_1 src1_sel:DWORD
	v_and_b32_sdwa v4, v22, v252 dst_sel:DWORD dst_unused:UNUSED_PAD src0_sel:WORD_1 src1_sel:DWORD
	v_add3_u32 v3, v3, v5, s33
	v_add3_u32 v2, v2, v6, s33
	v_add3_u32 v4, v22, v4, s33
	v_add3_u32 v0, v23, v0, s33
	v_and_b32_e32 v3, 0xffff0000, v3
	v_and_b32_e32 v2, 0xffff0000, v2
	v_or_b32_sdwa v3, v3, v0 dst_sel:DWORD dst_unused:UNUSED_PAD src0_sel:DWORD src1_sel:WORD_1
	v_or_b32_sdwa v2, v2, v4 dst_sel:DWORD dst_unused:UNUSED_PAD src0_sel:DWORD src1_sel:WORD_1
	flat_store_dwordx2 v[18:19], v[2:3] offset:80
	flat_load_dwordx2 v[6:7], v[38:39] offset:1120
	s_nop 0
	global_load_dwordx4 v[2:5], v[36:37], off offset:192
	s_waitcnt vmcnt(0) lgkmcnt(0)
	v_lshlrev_b32_e32 v0, 16, v7
	v_lshlrev_b32_e32 v24, 16, v6
	v_mul_f32_e32 v8, 0xbfb8aa3b, v24
	v_mov_b32_e32 v22, v2
	v_mul_f32_e32 v2, 0xbfb8aa3b, v0
	v_exp_f32_e32 v8, v8
	v_exp_f32_e32 v9, v2
	v_mov_b32_e32 v23, v4
	v_and_b32_e32 v25, 0xffff0000, v7
	v_and_b32_e32 v26, 0xffff0000, v6
	v_pk_add_f32 v[8:9], v[8:9], 1.0 op_sel_hi:[1,0]
	v_mul_f32_e32 v6, 0xbfb8aa3b, v26
	v_div_scale_f32 v2, s[0:1], v9, v9, v0
	v_rcp_f32_e32 v4, v2
	v_exp_f32_e32 v6, v6
	v_pk_mul_f32 v[20:21], v[20:21], v[22:23]
	v_fma_f32 v7, -v2, v4, 1.0
	v_fmac_f32_e32 v4, v7, v4
	v_div_scale_f32 v7, vcc, v0, v9, v0
	v_mul_f32_e32 v10, v7, v4
	v_fma_f32 v12, -v2, v10, v7
	v_fmac_f32_e32 v10, v12, v4
	v_fma_f32 v2, -v2, v10, v7
	v_div_fmas_f32 v2, v2, v4, v10
	v_div_fixup_f32 v9, v2, v9, v0
	v_div_scale_f32 v0, s[0:1], v8, v8, v24
	v_rcp_f32_e32 v2, v0
	v_mov_b32_e32 v12, v11
	v_fma_f32 v4, -v0, v2, 1.0
	v_fmac_f32_e32 v2, v4, v2
	v_div_scale_f32 v4, vcc, v24, v8, v24
	v_mul_f32_e32 v7, v4, v2
	v_fma_f32 v10, -v0, v7, v4
	v_fmac_f32_e32 v7, v10, v2
	v_fma_f32 v0, -v0, v7, v4
	v_div_fmas_f32 v0, v0, v2, v7
	v_div_fixup_f32 v8, v0, v8, v24
	v_mul_f32_e32 v0, 0xbfb8aa3b, v25
	v_exp_f32_e32 v7, v0
	v_mov_b32_e32 v4, v3
	v_pk_mul_f32 v[2:3], v[12:13], v[4:5]
	v_pk_mul_f32 v[8:9], v[20:21], v[8:9]
	v_pk_add_f32 v[4:5], v[6:7], 1.0 op_sel_hi:[1,0]
	s_nop 0
	v_div_scale_f32 v0, s[0:1], v5, v5, v25
	v_rcp_f32_e32 v6, v0
	s_nop 0
	v_fma_f32 v7, -v0, v6, 1.0
	v_fmac_f32_e32 v6, v7, v6
	v_div_scale_f32 v7, vcc, v25, v5, v25
	v_mul_f32_e32 v10, v7, v6
	v_fma_f32 v11, -v0, v10, v7
	v_fmac_f32_e32 v10, v11, v6
	v_fma_f32 v0, -v0, v10, v7
	v_div_fmas_f32 v0, v0, v6, v10
	v_div_fixup_f32 v5, v0, v5, v25
	v_div_scale_f32 v0, s[0:1], v4, v4, v26
	v_rcp_f32_e32 v6, v0
	s_nop 0
	v_fma_f32 v7, -v0, v6, 1.0
	v_fmac_f32_e32 v6, v7, v6
	v_div_scale_f32 v7, vcc, v26, v4, v26
	v_mul_f32_e32 v10, v7, v6
	v_fma_f32 v11, -v0, v10, v7
	v_fmac_f32_e32 v10, v11, v6
	v_fma_f32 v0, -v0, v10, v7
	v_div_fmas_f32 v0, v0, v6, v10
	v_div_fixup_f32 v4, v0, v4, v26
	v_pk_mul_f32 v[2:3], v[2:3], v[4:5]
	v_and_b32_sdwa v0, v9, v252 dst_sel:DWORD dst_unused:UNUSED_PAD src0_sel:WORD_1 src1_sel:DWORD
	v_and_b32_sdwa v5, v3, v252 dst_sel:DWORD dst_unused:UNUSED_PAD src0_sel:WORD_1 src1_sel:DWORD
	v_and_b32_sdwa v6, v2, v252 dst_sel:DWORD dst_unused:UNUSED_PAD src0_sel:WORD_1 src1_sel:DWORD
	v_and_b32_sdwa v4, v8, v252 dst_sel:DWORD dst_unused:UNUSED_PAD src0_sel:WORD_1 src1_sel:DWORD
	v_add3_u32 v3, v3, v5, s33
	v_add3_u32 v2, v2, v6, s33
	v_add3_u32 v4, v8, v4, s33
	v_add3_u32 v0, v9, v0, s33
	v_and_b32_e32 v3, 0xffff0000, v3
	v_and_b32_e32 v2, 0xffff0000, v2
	v_or_b32_sdwa v3, v3, v0 dst_sel:DWORD dst_unused:UNUSED_PAD src0_sel:DWORD src1_sel:WORD_1
	v_or_b32_sdwa v2, v2, v4 dst_sel:DWORD dst_unused:UNUSED_PAD src0_sel:DWORD src1_sel:WORD_1
	flat_store_dwordx2 v[18:19], v[2:3] offset:96
	flat_load_dwordx2 v[2:3], v[38:39] offset:1136
	s_nop 0
	global_load_dwordx4 v[4:7], v[36:37], off offset:224
	v_mov_b32_e32 v10, v14
	v_mov_b32_e32 v11, v16
	v_mov_b32_e32 v16, v15
	s_waitcnt vmcnt(0) lgkmcnt(0)
; __device__ __forceinline__ unsigned pk2(float lo, float hi) { return f2bf(lo) | (f2bf(hi) << 16); }
; __device__ __forceinline__ float bflo(unsigned w) { return __uint_as_float(w << 16); }
; __device__ __forceinline__ float bfhi(unsigned w) { return __uint_as_float(w & 0xffff0000u); }
; __device__ __forceinline__ float bf1(bf16 h) { return __uint_as_float(((unsigned)h) << 16); }
; __device__ __forceinline__ float silu(float x) { return x / (1.f + __expf(-x)); }
; __device__ __forceinline__ void pool_item(const Args& A, const Ctx& C0, int l, int row0, int t0, int pos0, const float* hist, float* outpool) {
;     ...
; #pragma unroll
;     for (int dt = 0; dt < 2; ++dt)
; #pragma unroll
;         for (int rq = 0; rq < 4; ++rq) { const int cc = g * 128 + ddh * 64 + dt * 32 + 8 * rq + 4 * h;
;             const v2u gx = *(const v2u*)(U + row * DIN + C_GP + cc); const f32x4 sc = *(const f32x4*)(psc + cc);
;             const float o0 = acc[dt][4 * rq] * sc.x * silu(bflo(gx.x)), o1 = acc[dt][4 * rq + 1] * sc.y * silu(bfhi(gx.x)), o2 = acc[dt][4 * rq + 2] * sc.z * silu(bflo(gx.y)), o3 = acc[dt][4 * rq + 3] * sc.w * silu(bfhi(gx.y));
;             v2u o; o.x = pk2(o0, o1); o.y = pk2(o2, o3);
;             *(v2u*)(MIX + row * D + cc) = o; }
;     if (outpool) for (int idx = C.tid; idx < 15 * 512; idx += 512) { const int rr = idx >> 9, cc = idx & 511; outpool[idx] = bf1(P[(32 + rr) * PP + cc]); }
	v_lshlrev_b32_e32 v0, 16, v3
	v_lshlrev_b32_e32 v20, 16, v2
	v_mul_f32_e32 v8, 0xbfb8aa3b, v20
	v_and_b32_e32 v21, 0xffff0000, v3
	v_mul_f32_e32 v3, 0xbfb8aa3b, v0
	v_exp_f32_e32 v8, v8
	v_exp_f32_e32 v9, v3
	v_mov_b32_e32 v12, v4
	v_mov_b32_e32 v13, v6
	v_pk_mul_f32 v[10:11], v[10:11], v[12:13]
	v_pk_add_f32 v[8:9], v[8:9], 1.0 op_sel_hi:[1,0]
	v_and_b32_e32 v22, 0xffff0000, v2
	v_div_scale_f32 v3, s[0:1], v9, v9, v0
	v_rcp_f32_e32 v4, v3
	v_mul_f32_e32 v2, 0xbfb8aa3b, v22
	v_exp_f32_e32 v2, v2
	v_fma_f32 v6, -v3, v4, 1.0
	v_fmac_f32_e32 v4, v6, v4
	v_div_scale_f32 v6, vcc, v0, v9, v0
	v_mul_f32_e32 v12, v6, v4
	v_fma_f32 v13, -v3, v12, v6
	v_fmac_f32_e32 v12, v13, v4
	v_fma_f32 v3, -v3, v12, v6
	v_div_fmas_f32 v3, v3, v4, v12
	v_div_fixup_f32 v9, v3, v9, v0
	v_div_scale_f32 v0, s[0:1], v8, v8, v20
	v_rcp_f32_e32 v3, v0
	s_nop 0
	v_fma_f32 v4, -v0, v3, 1.0
	v_fmac_f32_e32 v3, v4, v3
	v_div_scale_f32 v4, vcc, v20, v8, v20
	v_mul_f32_e32 v6, v4, v3
	v_fma_f32 v12, -v0, v6, v4
	v_fmac_f32_e32 v6, v12, v3
	v_fma_f32 v0, -v0, v6, v4
	v_div_fmas_f32 v0, v0, v3, v6
	v_div_fixup_f32 v8, v0, v8, v20
	v_mul_f32_e32 v0, 0xbfb8aa3b, v21
	v_exp_f32_e32 v3, v0
	v_mov_b32_e32 v6, v5
	v_pk_mul_f32 v[4:5], v[16:17], v[6:7]
	v_pk_mul_f32 v[8:9], v[10:11], v[8:9]
	v_pk_add_f32 v[2:3], v[2:3], 1.0 op_sel_hi:[1,0]
	s_nop 0
	v_div_scale_f32 v0, s[0:1], v3, v3, v21
	v_rcp_f32_e32 v6, v0
	s_nop 0
	v_fma_f32 v7, -v0, v6, 1.0
	v_fmac_f32_e32 v6, v7, v6
	v_div_scale_f32 v7, vcc, v21, v3, v21
	v_mul_f32_e32 v10, v7, v6
	v_fma_f32 v11, -v0, v10, v7
	v_fmac_f32_e32 v10, v11, v6
	v_fma_f32 v0, -v0, v10, v7
	v_div_fmas_f32 v0, v0, v6, v10
	v_div_fixup_f32 v3, v0, v3, v21
	v_div_scale_f32 v0, s[0:1], v2, v2, v22
	v_rcp_f32_e32 v6, v0
	s_cselect_b64 s[0:1], -1, 0
	v_fma_f32 v7, -v0, v6, 1.0
	v_fmac_f32_e32 v6, v7, v6
	v_div_scale_f32 v7, vcc, v22, v2, v22
	v_mul_f32_e32 v10, v7, v6
	v_fma_f32 v11, -v0, v10, v7
	v_fmac_f32_e32 v10, v11, v6
	v_fma_f32 v0, -v0, v10, v7
	v_div_fmas_f32 v0, v0, v6, v10
	v_div_fixup_f32 v2, v0, v2, v22
	v_pk_mul_f32 v[2:3], v[4:5], v[2:3]
	v_and_b32_sdwa v0, v9, v252 dst_sel:DWORD dst_unused:UNUSED_PAD src0_sel:WORD_1 src1_sel:DWORD
	v_and_b32_sdwa v5, v3, v252 dst_sel:DWORD dst_unused:UNUSED_PAD src0_sel:WORD_1 src1_sel:DWORD
	v_and_b32_sdwa v6, v2, v252 dst_sel:DWORD dst_unused:UNUSED_PAD src0_sel:WORD_1 src1_sel:DWORD
	v_and_b32_sdwa v4, v8, v252 dst_sel:DWORD dst_unused:UNUSED_PAD src0_sel:WORD_1 src1_sel:DWORD
	v_add3_u32 v3, v3, v5, s33
	v_add3_u32 v2, v2, v6, s33
	v_add3_u32 v4, v8, v4, s33
	v_add3_u32 v0, v9, v0, s33
	v_and_b32_e32 v3, 0xffff0000, v3
	v_and_b32_e32 v2, 0xffff0000, v2
	v_cmp_gt_i32_e32 vcc, s2, v34
	v_or_b32_sdwa v3, v3, v0 dst_sel:DWORD dst_unused:UNUSED_PAD src0_sel:DWORD src1_sel:WORD_1
	v_or_b32_sdwa v2, v2, v4 dst_sel:DWORD dst_unused:UNUSED_PAD src0_sel:DWORD src1_sel:WORD_1
	s_and_b64 s[2:3], s[0:1], vcc
	flat_store_dwordx2 v[18:19], v[2:3] offset:112
	s_and_saveexec_b64 s[0:1], s[2:3]
	s_cbranch_execz .LBB0_766
	v_max_i32_e32 v2, 0x1c00, v34
	v_sub_u32_e32 v2, v2, v34
	v_and_b32_e32 v0, 0x1ff, v34
	v_add_u32_e32 v2, 0x1ff, v2
	s_movk_i32 s2, 0x1ff
	v_cmp_lt_u32_e32 vcc, s2, v2
	s_mov_b64 s[2:3], -1
	v_lshl_add_u32 v0, v0, 1, 0
	s_and_saveexec_b64 s[24:25], vcc
	s_cbranch_execz .LBB0_763
	v_lshrrev_b32_e32 v2, 9, v2
	v_add_u32_e32 v4, 1, v2
	v_and_b32_e32 v5, 0xfffffe, v4
	s_mov_b64 s[30:31], 0
	v_mov_b32_e32 v6, v5
	v_mov_b64_e32 v[2:3], v[34:35]
	s_movk_i32 s2, 0x410

; __device__ __forceinline__ float bf1(bf16 h) { return __uint_as_float(((unsigned)h) << 16); }
; __device__ __forceinline__ void phase_post(const Args& A, const Ctx& C0, int l, int nskip) {
;     ...
;     for (int row0 = (C.bid - nskip) * 8; row0 < M; row0 += (C.G - nskip) * 8) {
;         float o[8], v[8], gr[8], rk[8];
; #pragma unroll
;         for (int i = 0; i < 8; ++i) { const size_t row = (size_t)(row0 + i);
;             o[i] = ((const float*)(Ub + row * UPITCH_B + UXC_B))[c]; v[i] = SCN[row * 3072 + hd * 384 + 320 + C.lane];
;             gr[i] = bf1(U[row * DIN + C_GR + c]); rk[i] = RKB[row * 8 + hd]; }
.LBB0_1187:
	v_add_co_u32_e32 v10, vcc, 0xfffee000, v6
	s_add_u32 s0, s40, s2
	s_nop 0
	v_addc_co_u32_e32 v11, vcc, -1, v7, vcc
	global_load_dword v43, v[10:11], off offset:-3328
	v_lshl_add_u64 v[10:11], s[40:41], 0, v[4:5]
	v_add_co_u32_e32 v12, vcc, 0x256d7000, v10
	s_addc_u32 s1, s41, s3
	s_nop 0
	v_addc_co_u32_e32 v13, vcc, 0, v11, vcc
	flat_load_dword v44, v[12:13] offset:3584
	v_lshl_add_u64 v[12:13], s[40:41], 0, v[8:9]
	v_add_co_u32_e32 v14, vcc, 0xfc2a000, v12
	s_add_i32 s42, s42, s44
	s_nop 0
	v_addc_co_u32_e32 v15, vcc, 0, v13, vcc
	flat_load_ushort v45, v[14:15]
	v_mov_b32_e32 v15, s1
	s_add_u32 s2, s2, s50
	s_addc_u32 s3, s3, s51
	v_lshl_add_u64 v[4:5], v[4:5], 0, s[52:53]
	v_lshl_add_u64 v[8:9], v[8:9], 0, s[54:55]
	s_cmp_lt_i32 s42, 0x8100
	v_mov_b32_e32 v14, s0
	v_add_co_u32_e32 v14, vcc, 0x7984000, v14
	s_mov_b32 s0, 0xffff6000
	s_nop 0
	v_addc_co_u32_e32 v15, vcc, 0, v15, vcc
	v_add_co_u32_e32 v18, vcc, s96, v6
	flat_load_dword v46, v[14:15]
	flat_load_dword v42, v[14:15] offset:32
	flat_load_dword v38, v[14:15] offset:64
	flat_load_dword v34, v[14:15] offset:96
	flat_load_dword v30, v[14:15] offset:128
	flat_load_dword v24, v[14:15] offset:160
	v_addc_co_u32_e32 v19, vcc, -1, v7, vcc
	global_load_dword v40, v[18:19], off offset:-512
	v_add_co_u32_e32 v18, vcc, 0x256da000, v10
	s_nop 1
	v_addc_co_u32_e32 v19, vcc, 0, v11, vcc
	flat_load_dword v41, v[18:19] offset:3584
	v_add_co_u32_e32 v18, vcc, 0xfc2c000, v12
	s_nop 1
	v_addc_co_u32_e32 v19, vcc, 0, v13, vcc
	flat_load_ushort v39, v[18:19] offset:2816
	v_add_co_u32_e32 v18, vcc, 0xffff3000, v6
	v_addc_co_u32_e32 v19, vcc, -1, v7, vcc
	global_load_dword v36, v[18:19], off offset:-1792
	v_add_co_u32_e32 v18, vcc, 0x256dd000, v10
	s_nop 1
	v_addc_co_u32_e32 v19, vcc, 0, v11, vcc
	flat_load_dword v37, v[18:19] offset:3584
	v_add_co_u32_e32 v18, vcc, 0xfc2f000, v12
	s_nop 1
	v_addc_co_u32_e32 v19, vcc, 0, v13, vcc
	flat_load_ushort v35, v[18:19] offset:1536
	v_add_co_u32_e32 v18, vcc, s0, v6
	s_movk_i32 s0, 0x8000
	s_nop 0
	v_addc_co_u32_e32 v19, vcc, -1, v7, vcc
	global_load_dword v32, v[18:19], off offset:-3072
	v_add_co_u32_e32 v18, vcc, 0x256e0000, v10
	v_addc_co_u32_e32 v19, vcc, 0, v11, vcc
	flat_load_dword v33, v[18:19] offset:3584
	v_add_co_u32_e32 v18, vcc, 0xfc32000, v12
	s_nop 1
	v_addc_co_u32_e32 v19, vcc, 0, v13, vcc
	flat_load_ushort v31, v[18:19] offset:256
	v_add_co_u32_e32 v18, vcc, s0, v6
	s_movk_i32 s0, 0xe000
	s_nop 0
	v_addc_co_u32_e32 v19, vcc, -1, v7, vcc
	global_load_dword v28, v[18:19], off offset:-256
	v_add_co_u32_e32 v18, vcc, 0x256e3000, v10
	v_addc_co_u32_e32 v19, vcc, 0, v11, vcc
	flat_load_dword v29, v[18:19] offset:3584
	v_add_co_u32_e32 v18, vcc, 0xfc34000, v12
	s_nop 1
	v_addc_co_u32_e32 v19, vcc, 0, v13, vcc
	flat_load_ushort v27, v[18:19] offset:3072
	v_add_co_u32_e32 v18, vcc, 0xffffb000, v6
	v_addc_co_u32_e32 v19, vcc, -1, v7, vcc
	global_load_dword v22, v[18:19], off offset:-1536
	v_add_co_u32_e32 v18, vcc, 0x256e6000, v10
	s_nop 1
	v_addc_co_u32_e32 v19, vcc, 0, v11, vcc
	flat_load_dword v23, v[18:19] offset:3584
	v_add_co_u32_e32 v18, vcc, 0xfc37000, v12
	s_nop 1
	v_addc_co_u32_e32 v19, vcc, 0, v13, vcc
	flat_load_ushort v21, v[18:19] offset:1792
	v_add_co_u32_e32 v18, vcc, s0, v6
	v_addc_co_u32_e32 v19, vcc, -1, v7, vcc
	v_add_co_u32_e32 v48, vcc, 0x256e9000, v10
	global_load_dword v18, v[18:19], off offset:-2816
	s_nop 0
	v_addc_co_u32_e32 v49, vcc, 0, v11, vcc
	flat_load_dword v19, v[48:49] offset:3584
	v_add_co_u32_e32 v48, vcc, 0xfc3a000, v12
	s_nop 1
	v_addc_co_u32_e32 v49, vcc, 0, v13, vcc
	v_add_co_u32_e32 v10, vcc, 0x256ec000, v10
	flat_load_ushort v17, v[48:49] offset:512
	s_nop 0
	v_addc_co_u32_e32 v11, vcc, 0, v11, vcc
	flat_load_dword v20, v[14:15] offset:192
	global_load_dword v25, v[6:7], off
	flat_load_dword v26, v[10:11] offset:3584
	v_add_co_u32_e32 v10, vcc, 0xfc3c000, v12
	v_lshl_add_u64 v[6:7], v[6:7], 0, s[54:55]
	s_nop 0
	v_addc_co_u32_e32 v11, vcc, 0, v13, vcc
	flat_load_ushort v10, v[10:11] offset:3328
	s_waitcnt vmcnt(0) lgkmcnt(0)
	v_lshlrev_b32_e32 v45, 16, v45
	v_lshlrev_b32_e32 v39, 16, v39
	v_lshlrev_b32_e32 v35, 16, v35
	v_lshlrev_b32_e32 v31, 16, v31
	v_lshlrev_b32_e32 v27, 16, v27
	v_lshlrev_b32_e32 v21, 16, v21
	v_lshlrev_b32_e32 v17, 16, v17
	flat_load_dword v13, v[14:15] offset:224
	v_lshlrev_b32_e32 v12, 16, v10
	v_add_f32_dpp v10, v43, v43 quad_perm:[1,0,3,2] row_mask:0xf bank_mask:0xf bound_ctrl:1
	s_nop 1
	v_add_f32_dpp v10, v10, v10 quad_perm:[2,3,0,1] row_mask:0xf bank_mask:0xf bound_ctrl:1
	s_nop 1
	v_add_f32_dpp v10, v10, v10 row_half_mirror row_mask:0xf bank_mask:0xf bound_ctrl:1
	s_nop 1
	v_add_f32_dpp v10, v10, v10 row_mirror row_mask:0xf bank_mask:0xf bound_ctrl:1
	s_nop 0
	v_readlane_b32 s1, v10, 16
	v_readlane_b32 s0, v10, 0
	s_nop 0
	v_mov_b32_e32 v11, s1
	v_readlane_b32 s1, v10, 48
	v_add_f32_e32 v11, s0, v11
	v_readlane_b32 s0, v10, 32
	v_mov_b32_e32 v10, s1
	s_nop 0
	v_add_f32_e32 v10, s0, v10
	v_add_f32_e32 v10, v11, v10
	v_fmac_f32_e32 v43, 0xbc800000, v10
	v_mul_f32_e32 v10, v43, v43
	s_nop 1
	v_mov_b32_dpp v10, v10 quad_perm:[1,0,3,2] row_mask:0xf bank_mask:0xf bound_ctrl:1
	v_fmac_f32_e32 v10, v43, v43
	s_nop 1
	v_add_f32_dpp v10, v10, v10 quad_perm:[2,3,0,1] row_mask:0xf bank_mask:0xf bound_ctrl:1
	s_nop 1
	v_add_f32_dpp v10, v10, v10 row_half_mirror row_mask:0xf bank_mask:0xf bound_ctrl:1
	s_nop 1
	v_add_f32_dpp v10, v10, v10 row_mirror row_mask:0xf bank_mask:0xf bound_ctrl:1
	s_nop 0
	v_readlane_b32 s1, v10, 16
	v_readlane_b32 s0, v10, 0
	s_nop 0
	v_mov_b32_e32 v11, s1
	v_readlane_b32 s1, v10, 48
	v_add_f32_e32 v11, s0, v11
	v_readlane_b32 s0, v10, 32
	v_mov_b32_e32 v10, s1
; __device__ __forceinline__ unsigned f2bf(float f) { unsigned u = __builtin_bit_cast(unsigned, f); return (u + 0x7fffu + ((u >> 16) & 1u)) >> 16; }
; __device__ __forceinline__ float silu(float x) { return x / (1.f + __expf(-x)); }
; __device__ __forceinline__ void phase_post(const Args& A, const Ctx& C0, int l, int nskip) {
;     ...
;         for (int i = 0; i < 8; ++i) { const size_t row = (size_t)(row0 + i);
;             const float mean = wave_sum_l(o[i], C.lane) * (1.f / 64.f); const float dd = o[i] - mean; const float var = wave_sum_l(dd * dd, C.lane) * (1.f / 64.f);
;             const float y = dd * (1.f / sqrtf(var + LNX_EPS)) * lw + lb + rk[i] * v[i];
;             MIX[row * D + 1536 + c] = (bf16)f2bf(y * silu(gr[i])); }
	s_nop 0
	v_add_f32_e32 v10, s0, v10
	v_add_f32_e32 v10, v11, v10
	v_fmamk_f32 v10, v10, 0x3c800000, v50
	v_cmp_gt_f32_e32 vcc, s7, v10
	v_mul_f32_e32 v11, 0x4f800000, v10
	s_nop 0
	v_cndmask_b32_e32 v10, v10, v11, vcc
	v_sqrt_f32_e32 v11, v10
	s_nop 0
	v_add_u32_e32 v14, -1, v11
	v_fma_f32 v15, -v14, v11, v10
	v_cmp_ge_f32_e64 s[0:1], 0, v15
	v_add_u32_e32 v15, 1, v11
	s_nop 0
	v_cndmask_b32_e64 v14, v11, v14, s[0:1]
	v_fma_f32 v11, -v15, v11, v10
	v_cmp_lt_f32_e64 s[0:1], 0, v11
	s_nop 1
	v_cndmask_b32_e64 v11, v14, v15, s[0:1]
	v_mul_f32_e32 v14, 0x37800000, v11
	v_cndmask_b32_e32 v11, v11, v14, vcc
	v_cmp_class_f32_e32 vcc, v10, v207
	s_nop 1
	v_cndmask_b32_e32 v10, v11, v10, vcc
	v_div_scale_f32 v11, s[0:1], v10, v10, 1.0
	v_rcp_f32_e32 v14, v11
	s_nop 0
	v_fma_f32 v15, -v11, v14, 1.0
	v_fmac_f32_e32 v14, v15, v14
	v_div_scale_f32 v15, vcc, 1.0, v10, 1.0
	v_mul_f32_e32 v47, v15, v14
	v_fma_f32 v48, -v11, v47, v15
	v_fmac_f32_e32 v47, v48, v14
	v_fma_f32 v11, -v11, v47, v15
	v_div_fmas_f32 v11, v11, v14, v47
	v_div_fixup_f32 v10, v11, v10, 1.0
	v_mul_f32_e32 v11, 0xbfb8aa3b, v45
	v_exp_f32_e32 v11, v11
	v_mul_f32_e32 v10, v43, v10
	v_fma_f32 v10, v0, v10, v16
	v_fmac_f32_e32 v10, v44, v46
	v_add_f32_e32 v11, 1.0, v11
	v_div_scale_f32 v14, s[0:1], v11, v11, v45
	v_rcp_f32_e32 v15, v14
	s_mov_b32 s0, 0x7b28000
	v_fma_f32 v43, -v14, v15, 1.0
	v_fmac_f32_e32 v15, v43, v15
	v_div_scale_f32 v43, vcc, v45, v11, v45
	v_mul_f32_e32 v44, v43, v15
	v_fma_f32 v46, -v14, v44, v43
	v_fmac_f32_e32 v44, v46, v15
	v_fma_f32 v14, -v14, v44, v43
	v_div_fmas_f32 v14, v14, v15, v44
	v_div_fixup_f32 v11, v14, v11, v45
	v_mul_f32_e32 v10, v11, v10
	v_bfe_u32 v11, v10, 16, 1
	v_add3_u32 v43, v10, v11, s33
	v_lshl_add_u64 v[10:11], s[40:41], 0, v[2:3]
	v_add_co_u32_e32 v14, vcc, s0, v10
	v_lshl_add_u64 v[2:3], v[2:3], 0, s[46:47]
	s_nop 0
	v_addc_co_u32_e32 v15, vcc, 0, v11, vcc
	flat_store_short_d16_hi v[14:15], v43 offset:1280
	v_add_f32_dpp v14, v40, v40 quad_perm:[1,0,3,2] row_mask:0xf bank_mask:0xf bound_ctrl:1
	s_nop 1
	v_add_f32_dpp v14, v14, v14 quad_perm:[2,3,0,1] row_mask:0xf bank_mask:0xf bound_ctrl:1
	s_nop 1
	v_add_f32_dpp v14, v14, v14 row_half_mirror row_mask:0xf bank_mask:0xf bound_ctrl:1
	s_nop 1
	v_add_f32_dpp v14, v14, v14 row_mirror row_mask:0xf bank_mask:0xf bound_ctrl:1
	s_nop 0
	v_readlane_b32 s1, v14, 16
	v_readlane_b32 s0, v14, 0
	s_nop 0
	v_mov_b32_e32 v15, s1
	v_readlane_b32 s1, v14, 48
	v_add_f32_e32 v15, s0, v15
	v_readlane_b32 s0, v14, 32
	v_mov_b32_e32 v14, s1
	s_nop 0
	v_add_f32_e32 v14, s0, v14
	v_add_f32_e32 v14, v15, v14
	v_fmac_f32_e32 v40, 0xbc800000, v14
	v_mul_f32_e32 v14, v40, v40
	s_nop 1
	v_mov_b32_dpp v14, v14 quad_perm:[1,0,3,2] row_mask:0xf bank_mask:0xf bound_ctrl:1
	v_fmac_f32_e32 v14, v40, v40
	s_nop 1
	v_add_f32_dpp v14, v14, v14 quad_perm:[2,3,0,1] row_mask:0xf bank_mask:0xf bound_ctrl:1
	s_nop 1
	v_add_f32_dpp v14, v14, v14 row_half_mirror row_mask:0xf bank_mask:0xf bound_ctrl:1
	s_nop 1
	v_add_f32_dpp v14, v14, v14 row_mirror row_mask:0xf bank_mask:0xf bound_ctrl:1
	s_nop 0
	v_readlane_b32 s1, v14, 16
	v_readlane_b32 s0, v14, 0
	s_nop 0
	v_mov_b32_e32 v15, s1
	v_readlane_b32 s1, v14, 48
	v_add_f32_e32 v15, s0, v15
	v_readlane_b32 s0, v14, 32
	v_mov_b32_e32 v14, s1
	s_nop 0
	v_add_f32_e32 v14, s0, v14
	v_add_f32_e32 v14, v15, v14
	v_fmamk_f32 v14, v14, 0x3c800000, v50
	v_cmp_gt_f32_e32 vcc, s7, v14
	v_mul_f32_e32 v15, 0x4f800000, v14
	s_nop 0
	v_cndmask_b32_e32 v14, v14, v15, vcc
	v_sqrt_f32_e32 v15, v14
	s_nop 0
	v_add_u32_e32 v43, -1, v15
	v_fma_f32 v44, -v43, v15, v14
	v_cmp_ge_f32_e64 s[0:1], 0, v44
	v_add_u32_e32 v44, 1, v15
	s_nop 0
	v_cndmask_b32_e64 v43, v15, v43, s[0:1]
	v_fma_f32 v15, -v44, v15, v14
	v_cmp_lt_f32_e64 s[0:1], 0, v15
	s_nop 1
	v_cndmask_b32_e64 v15, v43, v44, s[0:1]
	v_mul_f32_e32 v43, 0x37800000, v15
	v_cndmask_b32_e32 v15, v15, v43, vcc
	v_cmp_class_f32_e32 vcc, v14, v207
	s_nop 1
	v_cndmask_b32_e32 v14, v15, v14, vcc
	v_div_scale_f32 v15, s[0:1], v14, v14, 1.0
	v_rcp_f32_e32 v43, v15
	s_nop 0
	v_fma_f32 v44, -v15, v43, 1.0
	v_fmac_f32_e32 v43, v44, v43
	v_div_scale_f32 v44, vcc, 1.0, v14, 1.0
	v_mul_f32_e32 v45, v44, v43
	v_fma_f32 v46, -v15, v45, v44
	v_fmac_f32_e32 v45, v46, v43
	v_fma_f32 v15, -v15, v45, v44
	v_div_fmas_f32 v15, v15, v43, v45
	v_div_fixup_f32 v14, v15, v14, 1.0
	v_mul_f32_e32 v15, 0xbfb8aa3b, v39
	v_exp_f32_e32 v15, v15
	v_mul_f32_e32 v14, v40, v14
	v_fma_f32 v14, v0, v14, v16
	v_fmac_f32_e32 v14, v41, v42
	v_add_f32_e32 v15, 1.0, v15
	v_div_scale_f32 v40, s[0:1], v15, v15, v39
	v_rcp_f32_e32 v41, v40
	s_mov_b32 s0, 0x7b29000
	v_fma_f32 v42, -v40, v41, 1.0
	v_fmac_f32_e32 v41, v42, v41
	v_div_scale_f32 v42, vcc, v39, v15, v39
	v_mul_f32_e32 v43, v42, v41
	v_fma_f32 v44, -v40, v43, v42
	v_fmac_f32_e32 v43, v44, v41
	v_fma_f32 v40, -v40, v43, v42
	v_div_fmas_f32 v40, v40, v41, v43
	v_div_fixup_f32 v15, v40, v15, v39
	v_mul_f32_e32 v14, v15, v14
	v_bfe_u32 v15, v14, 16, 1
	v_add3_u32 v39, v14, v15, s33
	v_add_co_u32_e32 v14, vcc, s0, v10
	s_nop 1
	v_addc_co_u32_e32 v15, vcc, 0, v11, vcc
	flat_store_short_d16_hi v[14:15], v39 offset:1280
	v_add_f32_dpp v14, v36, v36 quad_perm:[1,0,3,2] row_mask:0xf bank_mask:0xf bound_ctrl:1
	s_nop 1
	v_add_f32_dpp v14, v14, v14 quad_perm:[2,3,0,1] row_mask:0xf bank_mask:0xf bound_ctrl:1
	s_nop 1
	v_add_f32_dpp v14, v14, v14 row_half_mirror row_mask:0xf bank_mask:0xf bound_ctrl:1
	s_nop 1
	v_add_f32_dpp v14, v14, v14 row_mirror row_mask:0xf bank_mask:0xf bound_ctrl:1
	s_nop 0
	v_readlane_b32 s1, v14, 16
	v_readlane_b32 s0, v14, 0
	s_nop 0
	v_mov_b32_e32 v15, s1
	v_readlane_b32 s1, v14, 48
	v_add_f32_e32 v15, s0, v15
; __device__ __forceinline__ unsigned f2bf(float f) { unsigned u = __builtin_bit_cast(unsigned, f); return (u + 0x7fffu + ((u >> 16) & 1u)) >> 16; }
; __device__ __forceinline__ float silu(float x) { return x / (1.f + __expf(-x)); }
; __device__ __forceinline__ void phase_post(const Args& A, const Ctx& C0, int l, int nskip) {
;     ...
;         for (int i = 0; i < 8; ++i) { const size_t row = (size_t)(row0 + i);
;             const float mean = wave_sum_l(o[i], C.lane) * (1.f / 64.f); const float dd = o[i] - mean; const float var = wave_sum_l(dd * dd, C.lane) * (1.f / 64.f);
;             const float y = dd * (1.f / sqrtf(var + LNX_EPS)) * lw + lb + rk[i] * v[i];
;             MIX[row * D + 1536 + c] = (bf16)f2bf(y * silu(gr[i])); }
	v_readlane_b32 s0, v14, 32
	v_mov_b32_e32 v14, s1
	s_nop 0
	v_add_f32_e32 v14, s0, v14
	v_add_f32_e32 v14, v15, v14
	v_fmac_f32_e32 v36, 0xbc800000, v14
	v_mul_f32_e32 v14, v36, v36
	s_nop 1
	v_mov_b32_dpp v14, v14 quad_perm:[1,0,3,2] row_mask:0xf bank_mask:0xf bound_ctrl:1
	v_fmac_f32_e32 v14, v36, v36
	s_nop 1
	v_add_f32_dpp v14, v14, v14 quad_perm:[2,3,0,1] row_mask:0xf bank_mask:0xf bound_ctrl:1
	s_nop 1
	v_add_f32_dpp v14, v14, v14 row_half_mirror row_mask:0xf bank_mask:0xf bound_ctrl:1
	s_nop 1
	v_add_f32_dpp v14, v14, v14 row_mirror row_mask:0xf bank_mask:0xf bound_ctrl:1
	s_nop 0
	v_readlane_b32 s1, v14, 16
	v_readlane_b32 s0, v14, 0
	s_nop 0
	v_mov_b32_e32 v15, s1
	v_readlane_b32 s1, v14, 48
	v_add_f32_e32 v15, s0, v15
	v_readlane_b32 s0, v14, 32
	v_mov_b32_e32 v14, s1
	s_nop 0
	v_add_f32_e32 v14, s0, v14
	v_add_f32_e32 v14, v15, v14
	v_fmamk_f32 v14, v14, 0x3c800000, v50
	v_cmp_gt_f32_e32 vcc, s7, v14
	v_mul_f32_e32 v15, 0x4f800000, v14
	s_nop 0
	v_cndmask_b32_e32 v14, v14, v15, vcc
	v_sqrt_f32_e32 v15, v14
	s_nop 0
	v_add_u32_e32 v39, -1, v15
	v_fma_f32 v40, -v39, v15, v14
	v_cmp_ge_f32_e64 s[0:1], 0, v40
	v_add_u32_e32 v40, 1, v15
	s_nop 0
	v_cndmask_b32_e64 v39, v15, v39, s[0:1]
	v_fma_f32 v15, -v40, v15, v14
	v_cmp_lt_f32_e64 s[0:1], 0, v15
	s_nop 1
	v_cndmask_b32_e64 v15, v39, v40, s[0:1]
	v_mul_f32_e32 v39, 0x37800000, v15
	v_cndmask_b32_e32 v15, v15, v39, vcc
	v_cmp_class_f32_e32 vcc, v14, v207
	s_nop 1
	v_cndmask_b32_e32 v14, v15, v14, vcc
	v_div_scale_f32 v15, s[0:1], v14, v14, 1.0
	v_rcp_f32_e32 v39, v15
	s_nop 0
	v_fma_f32 v40, -v15, v39, 1.0
	v_fmac_f32_e32 v39, v40, v39
	v_div_scale_f32 v40, vcc, 1.0, v14, 1.0
	v_mul_f32_e32 v41, v40, v39
	v_fma_f32 v42, -v15, v41, v40
	v_fmac_f32_e32 v41, v42, v39
	v_fma_f32 v15, -v15, v41, v40
	v_div_fmas_f32 v15, v15, v39, v41
	v_div_fixup_f32 v14, v15, v14, 1.0
	v_mul_f32_e32 v15, 0xbfb8aa3b, v35
	v_exp_f32_e32 v15, v15
	v_mul_f32_e32 v14, v36, v14
	v_fma_f32 v14, v0, v14, v16
	v_fmac_f32_e32 v14, v37, v38
	v_add_f32_e32 v15, 1.0, v15
	v_div_scale_f32 v36, s[0:1], v15, v15, v35
	v_rcp_f32_e32 v37, v36
	s_mov_b32 s0, 0x7b2a000
	v_fma_f32 v38, -v36, v37, 1.0
	v_fmac_f32_e32 v37, v38, v37
	v_div_scale_f32 v38, vcc, v35, v15, v35
	v_mul_f32_e32 v39, v38, v37
	v_fma_f32 v40, -v36, v39, v38
	v_fmac_f32_e32 v39, v40, v37
	v_fma_f32 v36, -v36, v39, v38
	v_div_fmas_f32 v36, v36, v37, v39
	v_div_fixup_f32 v15, v36, v15, v35
	v_mul_f32_e32 v14, v15, v14
	v_bfe_u32 v15, v14, 16, 1
	v_add3_u32 v35, v14, v15, s33
	v_add_co_u32_e32 v14, vcc, s0, v10
	s_nop 1
	v_addc_co_u32_e32 v15, vcc, 0, v11, vcc
	flat_store_short_d16_hi v[14:15], v35 offset:1280
	v_add_f32_dpp v14, v32, v32 quad_perm:[1,0,3,2] row_mask:0xf bank_mask:0xf bound_ctrl:1
	s_nop 1
	v_add_f32_dpp v14, v14, v14 quad_perm:[2,3,0,1] row_mask:0xf bank_mask:0xf bound_ctrl:1
	s_nop 1
	v_add_f32_dpp v14, v14, v14 row_half_mirror row_mask:0xf bank_mask:0xf bound_ctrl:1
	s_nop 1
	v_add_f32_dpp v14, v14, v14 row_mirror row_mask:0xf bank_mask:0xf bound_ctrl:1
	s_nop 0
	v_readlane_b32 s1, v14, 16
	v_readlane_b32 s0, v14, 0
	s_nop 0
	v_mov_b32_e32 v15, s1
	v_readlane_b32 s1, v14, 48
	v_add_f32_e32 v15, s0, v15
	v_readlane_b32 s0, v14, 32
	v_mov_b32_e32 v14, s1
	s_nop 0
	v_add_f32_e32 v14, s0, v14
	v_add_f32_e32 v14, v15, v14
	v_fmac_f32_e32 v32, 0xbc800000, v14
	v_mul_f32_e32 v14, v32, v32
	s_nop 1
	v_mov_b32_dpp v14, v14 quad_perm:[1,0,3,2] row_mask:0xf bank_mask:0xf bound_ctrl:1
	v_fmac_f32_e32 v14, v32, v32
	s_nop 1
	v_add_f32_dpp v14, v14, v14 quad_perm:[2,3,0,1] row_mask:0xf bank_mask:0xf bound_ctrl:1
	s_nop 1
	v_add_f32_dpp v14, v14, v14 row_half_mirror row_mask:0xf bank_mask:0xf bound_ctrl:1
	s_nop 1
	v_add_f32_dpp v14, v14, v14 row_mirror row_mask:0xf bank_mask:0xf bound_ctrl:1
	s_nop 0
	v_readlane_b32 s1, v14, 16
	v_readlane_b32 s0, v14, 0
	s_nop 0
	v_mov_b32_e32 v15, s1
	v_readlane_b32 s1, v14, 48
	v_add_f32_e32 v15, s0, v15
	v_readlane_b32 s0, v14, 32
	v_mov_b32_e32 v14, s1
	s_nop 0
	v_add_f32_e32 v14, s0, v14
	v_add_f32_e32 v14, v15, v14
	v_fmamk_f32 v14, v14, 0x3c800000, v50
	v_cmp_gt_f32_e32 vcc, s7, v14
	v_mul_f32_e32 v15, 0x4f800000, v14
	s_nop 0
	v_cndmask_b32_e32 v14, v14, v15, vcc
	v_sqrt_f32_e32 v15, v14
	s_nop 0
	v_add_u32_e32 v35, -1, v15
	v_fma_f32 v36, -v35, v15, v14
	v_cmp_ge_f32_e64 s[0:1], 0, v36
	v_add_u32_e32 v36, 1, v15
	s_nop 0
	v_cndmask_b32_e64 v35, v15, v35, s[0:1]
	v_fma_f32 v15, -v36, v15, v14
	v_cmp_lt_f32_e64 s[0:1], 0, v15
	s_nop 1
	v_cndmask_b32_e64 v15, v35, v36, s[0:1]
	v_mul_f32_e32 v35, 0x37800000, v15
	v_cndmask_b32_e32 v15, v15, v35, vcc
	v_cmp_class_f32_e32 vcc, v14, v207
	s_nop 1
	v_cndmask_b32_e32 v14, v15, v14, vcc
	v_div_scale_f32 v15, s[0:1], v14, v14, 1.0
	v_rcp_f32_e32 v35, v15
	s_nop 0
	v_fma_f32 v36, -v15, v35, 1.0
	v_fmac_f32_e32 v35, v36, v35
	v_div_scale_f32 v36, vcc, 1.0, v14, 1.0
	v_mul_f32_e32 v37, v36, v35
	v_fma_f32 v38, -v15, v37, v36
	v_fmac_f32_e32 v37, v38, v35
	v_fma_f32 v15, -v15, v37, v36
	v_div_fmas_f32 v15, v15, v35, v37
	v_div_fixup_f32 v14, v15, v14, 1.0
	v_mul_f32_e32 v15, 0xbfb8aa3b, v31
	v_exp_f32_e32 v15, v15
	v_mul_f32_e32 v14, v32, v14
	v_fma_f32 v14, v0, v14, v16
	v_fmac_f32_e32 v14, v33, v34
	v_add_f32_e32 v15, 1.0, v15
	v_div_scale_f32 v32, s[0:1], v15, v15, v31
	v_rcp_f32_e32 v33, v32
	s_mov_b32 s0, 0x7b2b000
	v_fma_f32 v34, -v32, v33, 1.0
	v_fmac_f32_e32 v33, v34, v33
	v_div_scale_f32 v34, vcc, v31, v15, v31
	v_mul_f32_e32 v35, v34, v33
	v_fma_f32 v36, -v32, v35, v34
	v_fmac_f32_e32 v35, v36, v33
	v_fma_f32 v32, -v32, v35, v34
	v_div_fmas_f32 v32, v32, v33, v35
	v_div_fixup_f32 v15, v32, v15, v31
	v_mul_f32_e32 v14, v15, v14
	v_bfe_u32 v15, v14, 16, 1
; __device__ __forceinline__ unsigned f2bf(float f) { unsigned u = __builtin_bit_cast(unsigned, f); return (u + 0x7fffu + ((u >> 16) & 1u)) >> 16; }
; __device__ __forceinline__ float silu(float x) { return x / (1.f + __expf(-x)); }
; __device__ __forceinline__ void phase_post(const Args& A, const Ctx& C0, int l, int nskip) {
;     ...
;         for (int i = 0; i < 8; ++i) { const size_t row = (size_t)(row0 + i);
;             const float mean = wave_sum_l(o[i], C.lane) * (1.f / 64.f); const float dd = o[i] - mean; const float var = wave_sum_l(dd * dd, C.lane) * (1.f / 64.f);
;             const float y = dd * (1.f / sqrtf(var + LNX_EPS)) * lw + lb + rk[i] * v[i];
;             MIX[row * D + 1536 + c] = (bf16)f2bf(y * silu(gr[i])); }
	v_add3_u32 v31, v14, v15, s33
	v_add_co_u32_e32 v14, vcc, s0, v10
	s_nop 1
	v_addc_co_u32_e32 v15, vcc, 0, v11, vcc
	flat_store_short_d16_hi v[14:15], v31 offset:1280
	v_add_f32_dpp v14, v28, v28 quad_perm:[1,0,3,2] row_mask:0xf bank_mask:0xf bound_ctrl:1
	s_nop 1
	v_add_f32_dpp v14, v14, v14 quad_perm:[2,3,0,1] row_mask:0xf bank_mask:0xf bound_ctrl:1
	s_nop 1
	v_add_f32_dpp v14, v14, v14 row_half_mirror row_mask:0xf bank_mask:0xf bound_ctrl:1
	s_nop 1
	v_add_f32_dpp v14, v14, v14 row_mirror row_mask:0xf bank_mask:0xf bound_ctrl:1
	s_nop 0
	v_readlane_b32 s1, v14, 16
	v_readlane_b32 s0, v14, 0
	s_nop 0
	v_mov_b32_e32 v15, s1
	v_readlane_b32 s1, v14, 48
	v_add_f32_e32 v15, s0, v15
	v_readlane_b32 s0, v14, 32
	v_mov_b32_e32 v14, s1
	s_nop 0
	v_add_f32_e32 v14, s0, v14
	v_add_f32_e32 v14, v15, v14
	v_fmac_f32_e32 v28, 0xbc800000, v14
	v_mul_f32_e32 v14, v28, v28
	s_nop 1
	v_mov_b32_dpp v14, v14 quad_perm:[1,0,3,2] row_mask:0xf bank_mask:0xf bound_ctrl:1
	v_fmac_f32_e32 v14, v28, v28
	s_nop 1
	v_add_f32_dpp v14, v14, v14 quad_perm:[2,3,0,1] row_mask:0xf bank_mask:0xf bound_ctrl:1
	s_nop 1
	v_add_f32_dpp v14, v14, v14 row_half_mirror row_mask:0xf bank_mask:0xf bound_ctrl:1
	s_nop 1
	v_add_f32_dpp v14, v14, v14 row_mirror row_mask:0xf bank_mask:0xf bound_ctrl:1
	s_nop 0
	v_readlane_b32 s1, v14, 16
	v_readlane_b32 s0, v14, 0
	s_nop 0
	v_mov_b32_e32 v15, s1
	v_readlane_b32 s1, v14, 48
	v_add_f32_e32 v15, s0, v15
	v_readlane_b32 s0, v14, 32
	v_mov_b32_e32 v14, s1
	s_nop 0
	v_add_f32_e32 v14, s0, v14
	v_add_f32_e32 v14, v15, v14
	v_fmamk_f32 v14, v14, 0x3c800000, v50
	v_cmp_gt_f32_e32 vcc, s7, v14
	v_mul_f32_e32 v15, 0x4f800000, v14
	s_nop 0
	v_cndmask_b32_e32 v14, v14, v15, vcc
	v_sqrt_f32_e32 v15, v14
	s_nop 0
	v_add_u32_e32 v31, -1, v15
	v_fma_f32 v32, -v31, v15, v14
	v_cmp_ge_f32_e64 s[0:1], 0, v32
	v_add_u32_e32 v32, 1, v15
	s_nop 0
	v_cndmask_b32_e64 v31, v15, v31, s[0:1]
	v_fma_f32 v15, -v32, v15, v14
	v_cmp_lt_f32_e64 s[0:1], 0, v15
	s_nop 1
	v_cndmask_b32_e64 v15, v31, v32, s[0:1]
	v_mul_f32_e32 v31, 0x37800000, v15
	v_cndmask_b32_e32 v15, v15, v31, vcc
	v_cmp_class_f32_e32 vcc, v14, v207
	s_nop 1
	v_cndmask_b32_e32 v14, v15, v14, vcc
	v_div_scale_f32 v15, s[0:1], v14, v14, 1.0
	v_rcp_f32_e32 v31, v15
	s_nop 0
	v_fma_f32 v32, -v15, v31, 1.0
	v_fmac_f32_e32 v31, v32, v31
	v_div_scale_f32 v32, vcc, 1.0, v14, 1.0
	v_mul_f32_e32 v33, v32, v31
	v_fma_f32 v34, -v15, v33, v32
	v_fmac_f32_e32 v33, v34, v31
	v_fma_f32 v15, -v15, v33, v32
	v_div_fmas_f32 v15, v15, v31, v33
	v_div_fixup_f32 v14, v15, v14, 1.0
	v_mul_f32_e32 v15, 0xbfb8aa3b, v27
	v_exp_f32_e32 v15, v15
	v_mul_f32_e32 v14, v28, v14
	v_fma_f32 v14, v0, v14, v16
	v_fmac_f32_e32 v14, v29, v30
	v_add_f32_e32 v15, 1.0, v15
	v_div_scale_f32 v28, s[0:1], v15, v15, v27
	v_rcp_f32_e32 v29, v28
	s_mov_b32 s0, 0x7b2c000
	v_fma_f32 v30, -v28, v29, 1.0
	v_fmac_f32_e32 v29, v30, v29
	v_div_scale_f32 v30, vcc, v27, v15, v27
	v_mul_f32_e32 v31, v30, v29
	v_fma_f32 v32, -v28, v31, v30
	v_fmac_f32_e32 v31, v32, v29
	v_fma_f32 v28, -v28, v31, v30
	v_div_fmas_f32 v28, v28, v29, v31
	v_div_fixup_f32 v15, v28, v15, v27
	v_mul_f32_e32 v14, v15, v14
	v_bfe_u32 v15, v14, 16, 1
	v_add3_u32 v27, v14, v15, s33
	v_add_co_u32_e32 v14, vcc, s0, v10
	s_nop 1
	v_addc_co_u32_e32 v15, vcc, 0, v11, vcc
	flat_store_short_d16_hi v[14:15], v27 offset:1280
	v_add_f32_dpp v14, v22, v22 quad_perm:[1,0,3,2] row_mask:0xf bank_mask:0xf bound_ctrl:1
	s_nop 1
	v_add_f32_dpp v14, v14, v14 quad_perm:[2,3,0,1] row_mask:0xf bank_mask:0xf bound_ctrl:1
	s_nop 1
	v_add_f32_dpp v14, v14, v14 row_half_mirror row_mask:0xf bank_mask:0xf bound_ctrl:1
	s_nop 1
	v_add_f32_dpp v14, v14, v14 row_mirror row_mask:0xf bank_mask:0xf bound_ctrl:1
	s_nop 0
	v_readlane_b32 s1, v14, 16
	v_readlane_b32 s0, v14, 0
	s_nop 0
	v_mov_b32_e32 v15, s1
	v_readlane_b32 s1, v14, 48
	v_add_f32_e32 v15, s0, v15
	v_readlane_b32 s0, v14, 32
	v_mov_b32_e32 v14, s1
	s_nop 0
	v_add_f32_e32 v14, s0, v14
	v_add_f32_e32 v14, v15, v14
	v_fmac_f32_e32 v22, 0xbc800000, v14
	v_mul_f32_e32 v14, v22, v22
	s_nop 1
	v_mov_b32_dpp v14, v14 quad_perm:[1,0,3,2] row_mask:0xf bank_mask:0xf bound_ctrl:1
	v_fmac_f32_e32 v14, v22, v22
	s_nop 1
	v_add_f32_dpp v14, v14, v14 quad_perm:[2,3,0,1] row_mask:0xf bank_mask:0xf bound_ctrl:1
	s_nop 1
	v_add_f32_dpp v14, v14, v14 row_half_mirror row_mask:0xf bank_mask:0xf bound_ctrl:1
	s_nop 1
	v_add_f32_dpp v14, v14, v14 row_mirror row_mask:0xf bank_mask:0xf bound_ctrl:1
	s_nop 0
	v_readlane_b32 s1, v14, 16
	v_readlane_b32 s0, v14, 0
	s_nop 0
	v_mov_b32_e32 v15, s1
	v_readlane_b32 s1, v14, 48
	v_add_f32_e32 v15, s0, v15
	v_readlane_b32 s0, v14, 32
	v_mov_b32_e32 v14, s1
	s_nop 0
	v_add_f32_e32 v14, s0, v14
	v_add_f32_e32 v14, v15, v14
	v_fmamk_f32 v14, v14, 0x3c800000, v50
	v_cmp_gt_f32_e32 vcc, s7, v14
	v_mul_f32_e32 v15, 0x4f800000, v14
	s_nop 0
	v_cndmask_b32_e32 v14, v14, v15, vcc
	v_sqrt_f32_e32 v15, v14
	s_nop 0
	v_add_u32_e32 v27, -1, v15
	v_fma_f32 v28, -v27, v15, v14
	v_cmp_ge_f32_e64 s[0:1], 0, v28
	v_add_u32_e32 v28, 1, v15
	s_nop 0
	v_cndmask_b32_e64 v27, v15, v27, s[0:1]
	v_fma_f32 v15, -v28, v15, v14
	v_cmp_lt_f32_e64 s[0:1], 0, v15
	s_nop 1
	v_cndmask_b32_e64 v15, v27, v28, s[0:1]
	v_mul_f32_e32 v27, 0x37800000, v15
	v_cndmask_b32_e32 v15, v15, v27, vcc
	v_cmp_class_f32_e32 vcc, v14, v207
	s_nop 1
	v_cndmask_b32_e32 v14, v15, v14, vcc
	v_div_scale_f32 v15, s[0:1], v14, v14, 1.0
	v_rcp_f32_e32 v27, v15
	s_nop 0
	v_fma_f32 v28, -v15, v27, 1.0
	v_fmac_f32_e32 v27, v28, v27
	v_div_scale_f32 v28, vcc, 1.0, v14, 1.0
	v_mul_f32_e32 v29, v28, v27
	v_fma_f32 v30, -v15, v29, v28
	v_fmac_f32_e32 v29, v30, v27
	v_fma_f32 v15, -v15, v29, v28
; __device__ __forceinline__ unsigned f2bf(float f) { unsigned u = __builtin_bit_cast(unsigned, f); return (u + 0x7fffu + ((u >> 16) & 1u)) >> 16; }
; __device__ __forceinline__ float silu(float x) { return x / (1.f + __expf(-x)); }
; __device__ __forceinline__ void phase_post(const Args& A, const Ctx& C0, int l, int nskip) {
;     ...
;         for (int i = 0; i < 8; ++i) { const size_t row = (size_t)(row0 + i);
;             const float mean = wave_sum_l(o[i], C.lane) * (1.f / 64.f); const float dd = o[i] - mean; const float var = wave_sum_l(dd * dd, C.lane) * (1.f / 64.f);
;             const float y = dd * (1.f / sqrtf(var + LNX_EPS)) * lw + lb + rk[i] * v[i];
;             MIX[row * D + 1536 + c] = (bf16)f2bf(y * silu(gr[i])); }
	v_div_fmas_f32 v15, v15, v27, v29
	v_div_fixup_f32 v14, v15, v14, 1.0
	v_mul_f32_e32 v15, 0xbfb8aa3b, v21
	v_exp_f32_e32 v15, v15
	v_mul_f32_e32 v14, v22, v14
	v_fma_f32 v14, v0, v14, v16
	v_fmac_f32_e32 v14, v23, v24
	v_add_f32_e32 v15, 1.0, v15
	v_div_scale_f32 v22, s[0:1], v15, v15, v21
	v_rcp_f32_e32 v23, v22
	s_mov_b32 s0, 0x7b2d000
	v_fma_f32 v24, -v22, v23, 1.0
	v_fmac_f32_e32 v23, v24, v23
	v_div_scale_f32 v24, vcc, v21, v15, v21
	v_mul_f32_e32 v27, v24, v23
	v_fma_f32 v28, -v22, v27, v24
	v_fmac_f32_e32 v27, v28, v23
	v_fma_f32 v22, -v22, v27, v24
	v_div_fmas_f32 v22, v22, v23, v27
	v_div_fixup_f32 v15, v22, v15, v21
	v_mul_f32_e32 v14, v15, v14
	v_bfe_u32 v15, v14, 16, 1
	v_add3_u32 v21, v14, v15, s33
	v_add_co_u32_e32 v14, vcc, s0, v10
	s_nop 1
	v_addc_co_u32_e32 v15, vcc, 0, v11, vcc
	flat_store_short_d16_hi v[14:15], v21 offset:1280
	v_add_f32_dpp v14, v18, v18 quad_perm:[1,0,3,2] row_mask:0xf bank_mask:0xf bound_ctrl:1
	s_nop 1
	v_add_f32_dpp v14, v14, v14 quad_perm:[2,3,0,1] row_mask:0xf bank_mask:0xf bound_ctrl:1
	s_nop 1
	v_add_f32_dpp v14, v14, v14 row_half_mirror row_mask:0xf bank_mask:0xf bound_ctrl:1
	s_nop 1
	v_add_f32_dpp v14, v14, v14 row_mirror row_mask:0xf bank_mask:0xf bound_ctrl:1
	s_nop 0
	v_readlane_b32 s1, v14, 16
	v_readlane_b32 s0, v14, 0
	s_nop 0
	v_mov_b32_e32 v15, s1
	v_readlane_b32 s1, v14, 48
	v_add_f32_e32 v15, s0, v15
	v_readlane_b32 s0, v14, 32
	v_mov_b32_e32 v14, s1
	s_nop 0
	v_add_f32_e32 v14, s0, v14
	v_add_f32_e32 v14, v15, v14
	v_fmac_f32_e32 v18, 0xbc800000, v14
	v_mul_f32_e32 v14, v18, v18
	s_nop 1
	v_mov_b32_dpp v14, v14 quad_perm:[1,0,3,2] row_mask:0xf bank_mask:0xf bound_ctrl:1
	v_fmac_f32_e32 v14, v18, v18
	s_nop 1
	v_add_f32_dpp v14, v14, v14 quad_perm:[2,3,0,1] row_mask:0xf bank_mask:0xf bound_ctrl:1
	s_nop 1
	v_add_f32_dpp v14, v14, v14 row_half_mirror row_mask:0xf bank_mask:0xf bound_ctrl:1
	s_nop 1
	v_add_f32_dpp v14, v14, v14 row_mirror row_mask:0xf bank_mask:0xf bound_ctrl:1
	s_nop 0
	v_readlane_b32 s1, v14, 16
	v_readlane_b32 s0, v14, 0
	s_nop 0
	v_mov_b32_e32 v15, s1
	v_readlane_b32 s1, v14, 48
	v_add_f32_e32 v15, s0, v15
	v_readlane_b32 s0, v14, 32
	v_mov_b32_e32 v14, s1
	s_nop 0
	v_add_f32_e32 v14, s0, v14
	v_add_f32_e32 v14, v15, v14
	v_fmamk_f32 v14, v14, 0x3c800000, v50
	v_cmp_gt_f32_e32 vcc, s7, v14
	v_mul_f32_e32 v15, 0x4f800000, v14
	s_nop 0
	v_cndmask_b32_e32 v14, v14, v15, vcc
	v_sqrt_f32_e32 v15, v14
	s_nop 0
	v_add_u32_e32 v21, -1, v15
	v_fma_f32 v22, -v21, v15, v14
	v_cmp_ge_f32_e64 s[0:1], 0, v22
	v_add_u32_e32 v22, 1, v15
	s_nop 0
	v_cndmask_b32_e64 v21, v15, v21, s[0:1]
	v_fma_f32 v15, -v22, v15, v14
	v_cmp_lt_f32_e64 s[0:1], 0, v15
	s_nop 1
	v_cndmask_b32_e64 v15, v21, v22, s[0:1]
	v_mul_f32_e32 v21, 0x37800000, v15
	v_cndmask_b32_e32 v15, v15, v21, vcc
	v_cmp_class_f32_e32 vcc, v14, v207
	s_nop 1
	v_cndmask_b32_e32 v14, v15, v14, vcc
	v_div_scale_f32 v15, s[0:1], v14, v14, 1.0
	v_rcp_f32_e32 v21, v15
	s_nop 0
	v_fma_f32 v22, -v15, v21, 1.0
	v_fmac_f32_e32 v21, v22, v21
	v_div_scale_f32 v22, vcc, 1.0, v14, 1.0
	v_mul_f32_e32 v23, v22, v21
	v_fma_f32 v24, -v15, v23, v22
	v_fmac_f32_e32 v23, v24, v21
	v_fma_f32 v15, -v15, v23, v22
	v_div_fmas_f32 v15, v15, v21, v23
	v_div_fixup_f32 v14, v15, v14, 1.0
	v_mul_f32_e32 v15, 0xbfb8aa3b, v17
	v_exp_f32_e32 v15, v15
	v_mul_f32_e32 v14, v18, v14
	v_fma_f32 v14, v0, v14, v16
	v_fmac_f32_e32 v14, v19, v20
	v_add_f32_e32 v15, 1.0, v15
	v_div_scale_f32 v18, s[0:1], v15, v15, v17
	v_rcp_f32_e32 v19, v18
	s_mov_b32 s0, 0x7b2e000
	v_fma_f32 v20, -v18, v19, 1.0
	v_fmac_f32_e32 v19, v20, v19
	v_div_scale_f32 v20, vcc, v17, v15, v17
	v_mul_f32_e32 v21, v20, v19
	v_fma_f32 v22, -v18, v21, v20
	v_fmac_f32_e32 v21, v22, v19
	v_fma_f32 v18, -v18, v21, v20
	v_div_fmas_f32 v18, v18, v19, v21
	v_div_fixup_f32 v15, v18, v15, v17
	v_mul_f32_e32 v14, v15, v14
	v_bfe_u32 v15, v14, 16, 1
	v_add3_u32 v17, v14, v15, s33
	v_add_co_u32_e32 v14, vcc, s0, v10
	s_nop 1
	v_addc_co_u32_e32 v15, vcc, 0, v11, vcc
	flat_store_short_d16_hi v[14:15], v17 offset:1280
	v_add_f32_dpp v14, v25, v25 quad_perm:[1,0,3,2] row_mask:0xf bank_mask:0xf bound_ctrl:1
	s_nop 1
	v_add_f32_dpp v14, v14, v14 quad_perm:[2,3,0,1] row_mask:0xf bank_mask:0xf bound_ctrl:1
	s_nop 1
	v_add_f32_dpp v14, v14, v14 row_half_mirror row_mask:0xf bank_mask:0xf bound_ctrl:1
	s_nop 1
	v_add_f32_dpp v14, v14, v14 row_mirror row_mask:0xf bank_mask:0xf bound_ctrl:1
	s_nop 0
	v_readlane_b32 s1, v14, 16
	v_readlane_b32 s0, v14, 0
	s_nop 0
	v_mov_b32_e32 v15, s1
	v_readlane_b32 s1, v14, 48
	v_add_f32_e32 v15, s0, v15
	v_readlane_b32 s0, v14, 32
	v_mov_b32_e32 v14, s1
	s_nop 0
	v_add_f32_e32 v14, s0, v14
	v_add_f32_e32 v14, v15, v14
	v_fmac_f32_e32 v25, 0xbc800000, v14
	v_mul_f32_e32 v14, v25, v25
	s_nop 1
	v_mov_b32_dpp v14, v14 quad_perm:[1,0,3,2] row_mask:0xf bank_mask:0xf bound_ctrl:1
	v_fmac_f32_e32 v14, v25, v25
	s_nop 1
	v_add_f32_dpp v14, v14, v14 quad_perm:[2,3,0,1] row_mask:0xf bank_mask:0xf bound_ctrl:1
	s_nop 1
	v_add_f32_dpp v14, v14, v14 row_half_mirror row_mask:0xf bank_mask:0xf bound_ctrl:1
	s_nop 1
	v_add_f32_dpp v14, v14, v14 row_mirror row_mask:0xf bank_mask:0xf bound_ctrl:1
	s_nop 0
	v_readlane_b32 s1, v14, 16
	v_readlane_b32 s0, v14, 0
	s_nop 0
	v_mov_b32_e32 v15, s1
	v_readlane_b32 s1, v14, 48
	v_add_f32_e32 v15, s0, v15
	v_readlane_b32 s0, v14, 32
	v_mov_b32_e32 v14, s1
	s_nop 0
	v_add_f32_e32 v14, s0, v14
	v_add_f32_e32 v14, v15, v14
	v_fmamk_f32 v14, v14, 0x3c800000, v50
	v_cmp_gt_f32_e32 vcc, s7, v14
	v_mul_f32_e32 v15, 0x4f800000, v14
	s_nop 0
	v_cndmask_b32_e32 v14, v14, v15, vcc
	v_sqrt_f32_e32 v15, v14
	s_nop 0
	v_add_u32_e32 v17, -1, v15
	v_fma_f32 v18, -v17, v15, v14
	v_cmp_ge_f32_e64 s[0:1], 0, v18
	v_add_u32_e32 v18, 1, v15
	s_nop 0
	v_cndmask_b32_e64 v17, v15, v17, s[0:1]
	v_fma_f32 v15, -v18, v15, v14
	v_cmp_lt_f32_e64 s[0:1], 0, v15
	s_nop 1
	v_cndmask_b32_e64 v15, v17, v18, s[0:1]
	v_mul_f32_e32 v17, 0x37800000, v15
	v_cndmask_b32_e32 v15, v15, v17, vcc
	v_cmp_class_f32_e32 vcc, v14, v207
	s_nop 1
	v_cndmask_b32_e32 v14, v15, v14, vcc
	v_div_scale_f32 v15, s[0:1], v14, v14, 1.0
	v_rcp_f32_e32 v17, v15
	s_nop 0
	v_fma_f32 v18, -v15, v17, 1.0
	v_fmac_f32_e32 v17, v18, v17
	v_div_scale_f32 v18, vcc, 1.0, v14, 1.0
	v_mul_f32_e32 v19, v18, v17
	v_fma_f32 v20, -v15, v19, v18
	v_fmac_f32_e32 v19, v20, v17
	v_fma_f32 v15, -v15, v19, v18
	v_div_fmas_f32 v15, v15, v17, v19
	v_div_fixup_f32 v14, v15, v14, 1.0
	v_mul_f32_e32 v14, v25, v14
	v_fma_f32 v14, v0, v14, v16
	s_waitcnt vmcnt(0) lgkmcnt(0)
; __device__ __forceinline__ unsigned f2bf(float f) { unsigned u = __builtin_bit_cast(unsigned, f); return (u + 0x7fffu + ((u >> 16) & 1u)) >> 16; }
; __device__ __forceinline__ float silu(float x) { return x / (1.f + __expf(-x)); }
; __device__ __forceinline__ void phase_post(const Args& A, const Ctx& C0, int l, int nskip) {
;     ...
;             const float y = dd * (1.f / sqrtf(var + LNX_EPS)) * lw + lb + rk[i] * v[i];
;             MIX[row * D + 1536 + c] = (bf16)f2bf(y * silu(gr[i])); }
	v_fmac_f32_e32 v14, v26, v13
	v_mul_f32_e32 v13, 0xbfb8aa3b, v12
	v_exp_f32_e32 v13, v13
	s_nop 0
	v_add_f32_e32 v13, 1.0, v13
	v_div_scale_f32 v15, s[0:1], v13, v13, v12
	v_rcp_f32_e32 v17, v15
	s_mov_b32 s0, 0x7b2f000
	v_fma_f32 v18, -v15, v17, 1.0
	v_fmac_f32_e32 v17, v18, v17
	v_div_scale_f32 v18, vcc, v12, v13, v12
	v_mul_f32_e32 v19, v18, v17
	v_fma_f32 v20, -v15, v19, v18
	v_fmac_f32_e32 v19, v20, v17
	v_fma_f32 v15, -v15, v19, v18
	v_div_fmas_f32 v15, v15, v17, v19
	v_div_fixup_f32 v12, v15, v13, v12
	v_mul_f32_e32 v12, v12, v14
	v_bfe_u32 v13, v12, 16, 1
	v_add_co_u32_e32 v10, vcc, s0, v10
	v_add3_u32 v12, v12, v13, s33
	s_nop 0
	v_addc_co_u32_e32 v11, vcc, 0, v11, vcc
	flat_store_short_d16_hi v[10:11], v12 offset:1280
	s_cbranch_scc1 .LBB0_1187
